# plus: final LN via LDS-DMA prefetch, LoRA unit rotation, P3 LN loads hoisted (mod/gb/partials)
# speedup vs baseline: 1.0044x; 1.0044x over previous
;     ...
;         if (MODH) {
;             float s = 0.f;
; #pragma unroll
;             for (int j = 0; j < 8; ++j) s += (v[j].x + v[j].y) + (v[j].z + v[j].w);
;             const float mean = wave_sum(s) * (1.f / D); float s2 = 0.f;
; #pragma unroll
;             for (int j = 0; j < 8; ++j) { v[j] = v[j] - mean; s2 += (v[j].x * v[j].x + v[j].y * v[j].y) + (v[j].z * v[j].z + v[j].w * v[j].w); }
;             const float rstd = 1.f / sqrtf(wave_sum(s2) * (1.f / D) + LN_EPS);
.LBB0_405:
	s_or_b64 exec, exec, s[4:5]
	v_mov_b32_e32 v4, v32
	v_mov_b32_e32 v5, v26
	v_mov_b32_e32 v18, v33
	v_mov_b32_e32 v19, v27
	v_pk_add_f32 v[4:5], v[4:5], v[18:19]
	v_mov_b32_e32 v18, v34
	v_mov_b32_e32 v19, v28
	v_mov_b32_e32 v24, v35
	v_mov_b32_e32 v25, v29
	v_pk_add_f32 v[18:19], v[18:19], v[24:25]
	v_mov_b32_e32 v24, v36
	v_pk_add_f32 v[4:5], v[4:5], v[18:19]
	v_mov_b32_e32 v18, v37
	v_mov_b32_e32 v19, v38
	v_mov_b32_e32 v25, v39
	v_pk_add_f32 v[18:19], v[18:19], v[24:25]
	v_add_f32_e32 v3, 0, v4
	v_pk_add_f32 v[18:19], v[18:19], v[18:19] op_sel:[0,1] op_sel_hi:[1,0]
	v_add_f32_e32 v4, v3, v5
	v_add_f32_e32 v24, v20, v21
	v_add_f32_e32 v30, v22, v23
	v_mov_b32_e32 v5, v14
	v_mov_b32_e32 v19, v15
	v_mov_b32_e32 v25, v16
	v_mov_b32_e32 v31, v17
	v_pk_add_f32 v[4:5], v[4:5], v[18:19]
	v_pk_add_f32 v[18:19], v[24:25], v[30:31]
	v_mov_b32_e32 v24, v40
	v_pk_add_f32 v[4:5], v[4:5], v[18:19]
	v_mov_b32_e32 v18, v41
	v_mov_b32_e32 v19, v42
	v_mov_b32_e32 v25, v43
	v_pk_add_f32 v[18:19], v[18:19], v[24:25]
	v_pk_add_f32 v[4:5], v[4:5], v[4:5] op_sel:[0,1] op_sel_hi:[1,0]
	v_pk_add_f32 v[18:19], v[18:19], v[18:19] op_sel:[0,1] op_sel_hi:[1,0]
	v_add_f32_e32 v24, v6, v7
	v_add_f32_e32 v30, v8, v9
	v_mov_b32_e32 v5, v10
	v_mov_b32_e32 v19, v11
	v_mov_b32_e32 v25, v12
	v_mov_b32_e32 v31, v13
	v_pk_add_f32 v[4:5], v[4:5], v[18:19]
	v_pk_add_f32 v[18:19], v[24:25], v[30:31]
	s_nop 0
	v_pk_add_f32 v[4:5], v[4:5], v[18:19]
	s_nop 0
	v_add_f32_e32 v3, v4, v5
	v_mov_b32_e32 v4, v2
	s_nop 0
	v_add_f32_dpp v3, v3, v3 quad_perm:[1,0,3,2] row_mask:0xf bank_mask:0xf bound_ctrl:1
	s_nop 1
	v_add_f32_dpp v3, v3, v3 quad_perm:[2,3,0,1] row_mask:0xf bank_mask:0xf bound_ctrl:1
	s_nop 1
	v_add_f32_dpp v3, v3, v3 row_half_mirror row_mask:0xf bank_mask:0xf bound_ctrl:1
	s_nop 1
	v_add_f32_dpp v3, v3, v3 row_mirror row_mask:0xf bank_mask:0xf bound_ctrl:1
	s_nop 1
	v_mov_b32_dpp v4, v3 row_bcast:15 row_mask:0xa bank_mask:0xf
	v_add_f32_e32 v3, v3, v4
	v_mov_b32_e32 v4, v2
	s_nop 1
	v_mov_b32_dpp v4, v3 row_bcast:31 row_mask:0xc bank_mask:0xf
	v_add_f32_e32 v3, v3, v4
	s_nop 0
	v_readlane_b32 s4, v3, 63
	s_nop 1
	v_fmac_f32_e32 v35, s4, v224
	v_fmac_f32_e32 v33, s4, v224
	v_fma_f32 v34, s4, v224, v34
	v_fma_f32 v32, s4, v224, v32
	v_mul_f32_e32 v3, v33, v33
	v_mul_f32_e32 v4, v35, v35
	v_fmac_f32_e32 v3, v32, v32
	v_fmac_f32_e32 v4, v34, v34
	v_fmac_f32_e32 v29, s4, v224
	v_fmac_f32_e32 v27, s4, v224
	v_add_f32_e32 v3, v3, v4
	v_fma_f32 v28, s4, v224, v28
	v_fma_f32 v26, s4, v224, v26
	v_mul_f32_e32 v4, v27, v27
	v_mul_f32_e32 v5, v29, v29
	v_fmac_f32_e32 v4, v26, v26
	v_fmac_f32_e32 v5, v28, v28
	v_add_f32_e32 v4, v4, v5
	v_fmac_f32_e32 v39, s4, v224
	v_fmac_f32_e32 v37, s4, v224
	v_add_f32_e32 v3, v3, v4
	v_fma_f32 v38, s4, v224, v38
	v_fma_f32 v36, s4, v224, v36
	v_mul_f32_e32 v4, v37, v37
	v_mul_f32_e32 v5, v39, v39
	v_fmac_f32_e32 v4, v36, v36
	v_fmac_f32_e32 v5, v38, v38
	v_add_f32_e32 v4, v4, v5
	v_fmac_f32_e32 v23, s4, v224
	v_fmac_f32_e32 v21, s4, v224
	v_add_f32_e32 v3, v4, v3
	v_fma_f32 v22, s4, v224, v22
	v_fma_f32 v20, s4, v224, v20
	v_mul_f32_e32 v4, v21, v21
	v_mul_f32_e32 v5, v23, v23
	v_fmac_f32_e32 v4, v20, v20
	v_fmac_f32_e32 v5, v22, v22
	v_add_f32_e32 v4, v4, v5
	v_fmac_f32_e32 v17, s4, v224
	v_fmac_f32_e32 v15, s4, v224
	v_add_f32_e32 v3, v4, v3
	v_fma_f32 v16, s4, v224, v16
	v_fma_f32 v14, s4, v224, v14
	v_mul_f32_e32 v4, v15, v15
	v_mul_f32_e32 v5, v17, v17
	v_fmac_f32_e32 v4, v14, v14
	v_fmac_f32_e32 v5, v16, v16
	v_add_f32_e32 v4, v4, v5
	v_fmac_f32_e32 v43, s4, v224
	v_fmac_f32_e32 v41, s4, v224
	v_add_f32_e32 v3, v4, v3
	v_fma_f32 v42, s4, v224, v42
	v_fma_f32 v40, s4, v224, v40
	v_mul_f32_e32 v4, v41, v41
	v_mul_f32_e32 v5, v43, v43
	v_fmac_f32_e32 v4, v40, v40
	v_fmac_f32_e32 v5, v42, v42
	v_add_f32_e32 v4, v4, v5
	v_fmac_f32_e32 v9, s4, v224
	v_fmac_f32_e32 v7, s4, v224
	v_add_f32_e32 v3, v4, v3
	v_fma_f32 v8, s4, v224, v8
	v_fma_f32 v6, s4, v224, v6
	v_mul_f32_e32 v4, v7, v7
	v_mul_f32_e32 v5, v9, v9
	v_fmac_f32_e32 v4, v6, v6
	v_fmac_f32_e32 v5, v8, v8
	v_add_f32_e32 v4, v4, v5
	v_fmac_f32_e32 v13, s4, v224
	v_fmac_f32_e32 v11, s4, v224
	v_add_f32_e32 v3, v4, v3
	v_fma_f32 v12, s4, v224, v12
	v_fma_f32 v10, s4, v224, v10
	v_mul_f32_e32 v4, v11, v11
	v_mul_f32_e32 v5, v13, v13
	v_fmac_f32_e32 v4, v10, v10
	v_fmac_f32_e32 v5, v12, v12
	v_add_f32_e32 v4, v4, v5
	v_add_f32_e32 v3, v4, v3
	v_mov_b32_e32 v4, v2
	s_nop 0
	v_add_f32_dpp v3, v3, v3 quad_perm:[1,0,3,2] row_mask:0xf bank_mask:0xf bound_ctrl:1
	s_nop 1
	v_add_f32_dpp v3, v3, v3 quad_perm:[2,3,0,1] row_mask:0xf bank_mask:0xf bound_ctrl:1
	s_nop 1
	v_add_f32_dpp v3, v3, v3 row_half_mirror row_mask:0xf bank_mask:0xf bound_ctrl:1
	s_nop 1
	v_add_f32_dpp v3, v3, v3 row_mirror row_mask:0xf bank_mask:0xf bound_ctrl:1
	s_nop 1
	v_mov_b32_dpp v4, v3 row_bcast:15 row_mask:0xa bank_mask:0xf
	v_add_f32_e32 v3, v3, v4
	v_mov_b32_e32 v4, v2
	s_nop 1
	v_mov_b32_dpp v4, v3 row_bcast:31 row_mask:0xc bank_mask:0xf
	v_add_f32_e32 v3, v3, v4
	s_nop 0
	v_readlane_b32 s4, v3, 63
	s_nop 1
	v_fma_f32 v3, s4, v226, v225
	v_cmp_gt_f32_e32 vcc, s73, v3
	v_mul_f32_e32 v4, 0x4f800000, v3
	s_nop 0
	v_cndmask_b32_e32 v3, v3, v4, vcc
	v_sqrt_f32_e32 v4, v3
	s_nop 0
	v_add_u32_e32 v5, -1, v4
	v_fma_f32 v18, -v5, v4, v3
	v_cmp_ge_f32_e64 s[4:5], 0, v18
	v_add_u32_e32 v18, 1, v4
	s_nop 0
	v_cndmask_b32_e64 v5, v4, v5, s[4:5]
	v_fma_f32 v4, -v18, v4, v3
	v_cmp_lt_f32_e64 s[4:5], 0, v4
	s_nop 1
	v_cndmask_b32_e64 v4, v5, v18, s[4:5]
	v_mul_f32_e32 v5, 0x37800000, v4
	v_cndmask_b32_e32 v4, v4, v5, vcc
	v_cmp_class_f32_e32 vcc, v3, v227
	s_nop 1
	v_cndmask_b32_e32 v3, v4, v3, vcc
	v_div_scale_f32 v4, s[4:5], v3, v3, 1.0
; __device__ __forceinline__ unsigned pk2(float lo, float hi) { const f32x2 v = {lo, hi}; return __builtin_bit_cast(unsigned, __builtin_convertvector(v, bf2n_t_)); }
;     ...
;             const float rstd = 1.f / sqrtf(wave_sum(s2) * (1.f / D) + LN_EPS);
;             const int bsel = m < ML ? (m >> 11) : 8;
;             const f32x4* shp = (const f32x4*)(mods_l + (size_t)bsel * 18432 + kshift * 2048);
;             const f32x4* scp = (const f32x4*)(mods_l + (size_t)bsel * 18432 + kscale * 2048);
;             v2u* hp = (v2u*)(HB + (size_t)m * D);
; #pragma unroll
;             for (int j = 0; j < 8; ++j) { const f32x4 sh = shp[F.lane + 64 * j], scl = scp[F.lane + 64 * j]; const f32x4 o = v[j] * rstd * (scl + 1.0f) + sh;
;                 v2u w; w.x = pk2(o.x, o.y); w.y = pk2(o.z, o.w); hp[F.lane + 64 * j] = w; }
	v_rcp_f32_e32 v5, v4
	s_min_i32 s4, s6, 0x4000
	s_ashr_i32 s4, s4, 11
	s_mul_hi_i32 s5, s4, 0x12000
	v_fma_f32 v18, -v4, v5, 1.0
	v_fmac_f32_e32 v5, v18, v5
	v_div_scale_f32 v18, vcc, 1.0, v3, 1.0
	s_mul_i32 s4, s4, 0x12000
	v_mul_f32_e32 v19, v18, v5
	s_add_u32 s4, s10, s4
	v_fma_f32 v24, -v4, v19, v18
	s_addc_u32 s5, s11, s5
	v_fmac_f32_e32 v19, v24, v5
	v_lshl_add_u64 v[24:25], v[0:1], 4, s[4:5]
	s_mov_b64 s[4:5], 0x6000
	v_fma_f32 v4, -v4, v19, v18
	v_lshl_add_u64 v[30:31], v[24:25], 0, s[4:5]
	s_movk_i32 s4, 0x7000
	v_div_fmas_f32 v4, v4, v5, v19
	v_add_co_u32_e32 v18, vcc, s4, v24
	s_mov_b64 s[4:5], 0x8000
	s_nop 0
	v_addc_co_u32_e32 v19, vcc, 0, v25, vcc
	v_lshl_add_u64 v[94:95], v[24:25], 0, s[4:5]
	v_add_co_u32_e32 v24, vcc, s38, v24
	global_load_dwordx4 v[44:47], v[18:19], off offset:-4096
	s_nop 0
	v_addc_co_u32_e32 v25, vcc, 0, v25, vcc
	global_load_dwordx4 v[48:51], v[24:25], off offset:-4096
	global_load_dwordx4 v[104:107], v[30:31], off offset:1024
	global_load_dwordx4 v[108:111], v[94:95], off offset:1024
	global_load_dwordx4 v[112:115], v[30:31], off offset:2048
	global_load_dwordx4 v[116:119], v[94:95], off offset:2048
	global_load_dwordx4 v[120:123], v[30:31], off offset:3072
	global_load_dwordx4 v[124:127], v[94:95], off offset:3072
	global_load_dwordx4 v[128:131], v[18:19], off
	global_load_dwordx4 v[132:135], v[24:25], off
	global_load_dwordx4 v[136:139], v[18:19], off offset:1024
	global_load_dwordx4 v[140:143], v[24:25], off offset:1024
	global_load_dwordx4 v[144:147], v[18:19], off offset:2048
	global_load_dwordx4 v[148:151], v[24:25], off offset:2048
	global_load_dwordx4 v[152:155], v[18:19], off offset:3072
	global_load_dwordx4 v[156:159], v[24:25], off offset:3072
	v_div_fixup_f32 v4, v4, v3, 1.0
	v_pk_mul_f32 v[32:33], v[32:33], v[4:5] op_sel_hi:[1,0]
	v_pk_mul_f32 v[34:35], v[34:35], v[4:5] op_sel_hi:[1,0]
	v_pk_mul_f32 v[26:27], v[26:27], v[4:5] op_sel_hi:[1,0]
	v_pk_mul_f32 v[28:29], v[28:29], v[4:5] op_sel_hi:[1,0]
	v_pk_mul_f32 v[36:37], v[36:37], v[4:5] op_sel_hi:[1,0]
	v_pk_mul_f32 v[38:39], v[38:39], v[4:5] op_sel_hi:[1,0]
	v_pk_mul_f32 v[20:21], v[20:21], v[4:5] op_sel_hi:[1,0]
	v_pk_mul_f32 v[22:23], v[22:23], v[4:5] op_sel_hi:[1,0]
	v_pk_mul_f32 v[14:15], v[14:15], v[4:5] op_sel_hi:[1,0]
	v_pk_mul_f32 v[16:17], v[16:17], v[4:5] op_sel_hi:[1,0]
	v_pk_mul_f32 v[6:7], v[6:7], v[4:5] op_sel_hi:[1,0]
	v_pk_mul_f32 v[8:9], v[8:9], v[4:5] op_sel_hi:[1,0]
	v_pk_mul_f32 v[10:11], v[10:11], v[4:5] op_sel_hi:[1,0]
	s_add_u32 s6, s6, s12
	s_addc_u32 s7, s7, s13
	s_add_i32 s18, s18, s33
	s_cmpk_lt_i32 s6, 0x4800
	s_waitcnt vmcnt(14)
	v_pk_add_f32 v[50:51], v[50:51], 1.0 op_sel_hi:[1,0]
	v_pk_add_f32 v[48:49], v[48:49], 1.0 op_sel_hi:[1,0]
	v_pk_fma_f32 v[34:35], v[50:51], v[34:35], v[46:47]
	v_pk_fma_f32 v[32:33], v[48:49], v[32:33], v[44:45]
	s_nop 0
	v_cvt_pk_bf16_f32 v32, v32, v33
	v_cvt_pk_bf16_f32 v33, v34, v35
	global_store_dwordx2 v[92:93], v[32:33], off
	s_nop 0
	s_nop 0
	s_nop 0
	s_waitcnt vmcnt(13)
	v_pk_add_f32 v[46:47], v[110:111], 1.0 op_sel_hi:[1,0]
	v_pk_add_f32 v[44:45], v[108:109], 1.0 op_sel_hi:[1,0]
	v_pk_fma_f32 v[28:29], v[46:47], v[28:29], v[106:107]
	v_pk_fma_f32 v[26:27], v[44:45], v[26:27], v[104:105]
	s_nop 0
	v_cvt_pk_bf16_f32 v26, v26, v27
	v_cvt_pk_bf16_f32 v27, v28, v29
	global_store_dwordx2 v[92:93], v[26:27], off offset:512
	s_nop 0
	s_nop 0
	s_nop 0
	s_waitcnt vmcnt(12)
	v_pk_add_f32 v[34:35], v[118:119], 1.0 op_sel_hi:[1,0]
	v_pk_add_f32 v[32:33], v[116:117], 1.0 op_sel_hi:[1,0]
	v_pk_fma_f32 v[28:29], v[38:39], v[34:35], v[114:115]
	v_pk_fma_f32 v[26:27], v[36:37], v[32:33], v[112:113]
	s_nop 0
	v_cvt_pk_bf16_f32 v26, v26, v27
	v_cvt_pk_bf16_f32 v27, v28, v29
	global_store_dwordx2 v[92:93], v[26:27], off offset:1024
	s_nop 0
	s_nop 0
	s_nop 0
	s_waitcnt vmcnt(11)
	v_pk_add_f32 v[32:33], v[126:127], 1.0 op_sel_hi:[1,0]
	v_pk_add_f32 v[30:31], v[124:125], 1.0 op_sel_hi:[1,0]
	v_pk_fma_f32 v[22:23], v[22:23], v[32:33], v[122:123]
	v_pk_fma_f32 v[20:21], v[20:21], v[30:31], v[120:121]
	s_nop 0
	v_cvt_pk_bf16_f32 v20, v20, v21
	v_cvt_pk_bf16_f32 v21, v22, v23
	global_store_dwordx2 v[92:93], v[20:21], off offset:1536
	s_nop 0
	s_nop 0
	s_nop 0
	s_waitcnt vmcnt(10)
	v_pk_add_f32 v[28:29], v[134:135], 1.0 op_sel_hi:[1,0]
	v_pk_add_f32 v[26:27], v[132:133], 1.0 op_sel_hi:[1,0]
	v_pk_fma_f32 v[16:17], v[16:17], v[28:29], v[130:131]
	v_pk_fma_f32 v[14:15], v[14:15], v[26:27], v[128:129]
	v_pk_mul_f32 v[26:27], v[40:41], v[4:5] op_sel_hi:[1,0]
	v_cvt_pk_bf16_f32 v14, v14, v15
	v_cvt_pk_bf16_f32 v15, v16, v17
	global_store_dwordx2 v[92:93], v[14:15], off offset:2048
	s_nop 0
	s_nop 0
	s_nop 0
	v_pk_mul_f32 v[28:29], v[42:43], v[4:5] op_sel_hi:[1,0]
	v_pk_mul_f32 v[4:5], v[12:13], v[4:5] op_sel_hi:[1,0]
	s_waitcnt vmcnt(9)
	v_pk_add_f32 v[22:23], v[142:143], 1.0 op_sel_hi:[1,0]
	v_pk_add_f32 v[20:21], v[140:141], 1.0 op_sel_hi:[1,0]
	v_pk_fma_f32 v[16:17], v[28:29], v[22:23], v[138:139]
	v_pk_fma_f32 v[14:15], v[26:27], v[20:21], v[136:137]
	s_nop 0
	v_cvt_pk_bf16_f32 v14, v14, v15
	v_cvt_pk_bf16_f32 v15, v16, v17
	global_store_dwordx2 v[92:93], v[14:15], off offset:2560
	s_nop 0
	s_nop 0
	s_nop 0
	s_waitcnt vmcnt(8)
	v_pk_add_f32 v[22:23], v[150:151], 1.0 op_sel_hi:[1,0]
	v_pk_add_f32 v[20:21], v[148:149], 1.0 op_sel_hi:[1,0]
	v_pk_fma_f32 v[8:9], v[8:9], v[22:23], v[146:147]
	v_pk_fma_f32 v[6:7], v[6:7], v[20:21], v[144:145]
	s_nop 0
	v_cvt_pk_bf16_f32 v6, v6, v7
	v_cvt_pk_bf16_f32 v7, v8, v9
	global_store_dwordx2 v[92:93], v[6:7], off offset:3072
	s_nop 0
	s_nop 0
	s_nop 0
	s_waitcnt vmcnt(7)
	v_pk_add_f32 v[12:13], v[158:159], 1.0 op_sel_hi:[1,0]
	v_pk_add_f32 v[14:15], v[156:157], 1.0 op_sel_hi:[1,0]
	v_pk_fma_f32 v[4:5], v[4:5], v[12:13], v[154:155]
	v_pk_fma_f32 v[6:7], v[10:11], v[14:15], v[152:153]
	s_nop 0
	v_cvt_pk_bf16_f32 v6, v6, v7
	v_cvt_pk_bf16_f32 v7, v4, v5
	global_store_dwordx2 v[92:93], v[6:7], off offset:3584
	v_lshl_add_u64 v[92:93], v[92:93], 0, s[20:21]
	s_cbranch_scc0 .LBB0_427
; __device__ __forceinline__ float* xrow(const Frame& F, int m) { return m < ML ? (float*)(F.out + (size_t)m * D) : WSP(float, WS_XC) + (size_t)(m - ML) * D; }
;     ...
;         float* xr = xrow(F, m);
;         const float* xs = (m < ML) ? (src_l ? src_l + (size_t)m * D : xr) : (src_c ? src_c + (size_t)(m - ML) * D : xr);
;         f32x4 v[8];
; #pragma unroll
;         for (int j = 0; j < 8; ++j) v[j] = ((const f32x4*)xs)[F.lane + 64 * j];
;         if (POST && part != nullptr && m >= ML) {
;             const v2u* pp = (const v2u*)(part + (size_t)(m - ML) * D);
; #pragma unroll
;             for (int j = 0; j < 8; ++j) { const int o = F.lane + 64 * j; const v2u p0 = pp[o], p1 = pp[o + (size_t)MC * D / 4], p2 = pp[o + 2 * ((size_t)MC * D / 4)], p3 = pp[o + 3 * ((size_t)MC * D / 4)];
;                 const f32x4 ps = ((f32x4){bflo(p0.x), bfhi(p0.x), bflo(p0.y), bfhi(p0.y)} + (f32x4){bflo(p1.x), bfhi(p1.x), bflo(p1.y), bfhi(p1.y)}) + ((f32x4){bflo(p2.x), bfhi(p2.x), bflo(p2.y), bfhi(p2.y)} + (f32x4){bflo(p3.x), bfhi(p3.x), bflo(p3.y), bfhi(p3.y)});
;                 v[j] = v[j] * ALPHA + ((const f32x4*)pmod)[o] * pcoef * ps; }
.LBB0_406:
	s_add_i32 s66, s6, 0xffffc000
	s_cmpk_lt_i32 s6, 0x4000
	s_cselect_b64 s[22:23], -1, 0
	s_and_b64 s[4:5], s[22:23], exec
	s_cselect_b32 s5, s7, 0
	s_cselect_b32 s4, s6, s66
	s_cselect_b32 s19, s1, s29
	s_cselect_b32 s24, s0, s28
	s_lshl_b64 s[4:5], s[4:5], 13
	s_add_u32 s24, s24, s4
	s_addc_u32 s25, s19, s5
	s_or_b64 s[4:5], s[14:15], s[22:23]
	s_lshl_b64 s[26:27], s[66:67], 13
	s_add_u32 s19, s8, s26
	s_addc_u32 s26, s9, s27
	s_and_b64 s[4:5], s[4:5], exec
	s_cselect_b32 s4, s25, s26
	s_cselect_b32 s5, s24, s19
	v_mov_b32_e32 v4, s5
	v_mov_b32_e32 v5, s4
	v_lshl_add_u64 v[4:5], v[0:1], 4, v[4:5]
	global_load_dwordx4 v[28:31], v[4:5], off
	global_load_dwordx4 v[32:35], v[4:5], off offset:1024
	global_load_dwordx4 v[24:27], v[4:5], off offset:2048
	global_load_dwordx4 v[20:23], v[4:5], off offset:3072
	v_add_co_u32_e32 v4, vcc, 0x1000, v4
	s_cmpk_gt_i32 s6, 0x3fff
	s_nop 0
	v_addc_co_u32_e32 v5, vcc, 0, v5, vcc
	global_load_dwordx4 v[16:19], v[4:5], off
	global_load_dwordx4 v[12:15], v[4:5], off offset:1024
	global_load_dwordx4 v[8:11], v[4:5], off offset:2048
	s_nop 0
	global_load_dwordx4 v[4:7], v[4:5], off offset:3072
	s_cselect_b64 s[26:27], -1, 0
	s_and_b64 s[4:5], s[16:17], s[26:27]
	s_andn2_b64 vcc, exec, s[4:5]
	s_cbranch_vccnz .LBB0_408
	s_lshl_b64 s[4:5], s[66:67], 12
	v_lshl_add_u64 v[46:47], v[90:91], 0, s[4:5]
	v_add_co_u32_e32 v44, vcc, 0x800000, v46
	global_load_dwordx2 v[36:37], v[46:47], off
	s_nop 0
	v_addc_co_u32_e32 v45, vcc, 0, v47, vcc
	v_add_co_u32_e32 v42, vcc, 0x1000000, v46
	global_load_dwordx2 v[38:39], v[44:45], off
	s_nop 0
	v_addc_co_u32_e32 v43, vcc, 0, v47, vcc
	v_add_co_u32_e32 v40, vcc, 0x1800000, v46
	global_load_dwordx2 v[48:49], v[42:43], off
	s_nop 0
	v_addc_co_u32_e32 v41, vcc, 0, v47, vcc
	global_load_dwordx2 v[50:51], v[40:41], off
	global_load_dwordx4 v[104:107], v[80:81], off
	global_load_dwordx2 v[136:137], v[46:47], off offset:512
	global_load_dwordx2 v[138:139], v[44:45], off offset:512
	global_load_dwordx2 v[140:141], v[42:43], off offset:512
	global_load_dwordx2 v[142:143], v[40:41], off offset:512
	global_load_dwordx4 v[108:111], v[80:81], off offset:1024
	global_load_dwordx2 v[144:145], v[46:47], off offset:1024
	global_load_dwordx2 v[146:147], v[44:45], off offset:1024
	global_load_dwordx2 v[148:149], v[42:43], off offset:1024
	global_load_dwordx2 v[150:151], v[40:41], off offset:1024
	global_load_dwordx4 v[112:115], v[80:81], off offset:2048
	global_load_dwordx2 v[152:153], v[46:47], off offset:1536
	global_load_dwordx2 v[154:155], v[44:45], off offset:1536
	global_load_dwordx2 v[156:157], v[42:43], off offset:1536
	global_load_dwordx2 v[158:159], v[40:41], off offset:1536
	global_load_dwordx4 v[116:119], v[80:81], off offset:3072
	global_load_dwordx2 v[160:161], v[46:47], off offset:2048
	global_load_dwordx2 v[162:163], v[44:45], off offset:2048
	global_load_dwordx2 v[164:165], v[42:43], off offset:2048
	global_load_dwordx2 v[166:167], v[40:41], off offset:2048
	global_load_dwordx4 v[120:123], v[82:83], off
	global_load_dwordx2 v[168:169], v[46:47], off offset:2560
	global_load_dwordx2 v[170:171], v[44:45], off offset:2560
	global_load_dwordx2 v[172:173], v[42:43], off offset:2560
	global_load_dwordx2 v[174:175], v[40:41], off offset:2560
	global_load_dwordx4 v[124:127], v[84:85], off
	global_load_dwordx2 v[176:177], v[46:47], off offset:3072
	global_load_dwordx2 v[178:179], v[44:45], off offset:3072
	global_load_dwordx2 v[180:181], v[42:43], off offset:3072
	global_load_dwordx2 v[182:183], v[40:41], off offset:3072
	global_load_dwordx4 v[128:131], v[86:87], off
	global_load_dwordx2 v[184:185], v[46:47], off offset:3584
	global_load_dwordx2 v[186:187], v[44:45], off offset:3584
	global_load_dwordx2 v[188:189], v[42:43], off offset:3584
	global_load_dwordx2 v[190:191], v[40:41], off offset:3584
	global_load_dwordx4 v[132:135], v[88:89], off
	s_mov_b32 s4, 0x3fb504f3
	s_waitcnt vmcnt(36)
	v_lshlrev_b32_e32 v94, 16, v36
	v_and_b32_e32 v95, 0xffff0000, v36
	v_lshlrev_b32_e32 v36, 16, v37
	v_and_b32_e32 v37, 0xffff0000, v37
	v_lshlrev_b32_e32 v96, 16, v38
	v_and_b32_e32 v97, 0xffff0000, v38
	v_lshlrev_b32_e32 v38, 16, v39
	v_and_b32_e32 v39, 0xffff0000, v39
	v_pk_add_f32 v[94:95], v[94:95], v[96:97]
	v_pk_add_f32 v[36:37], v[36:37], v[38:39]
	v_lshlrev_b32_e32 v38, 16, v48
	v_and_b32_e32 v39, 0xffff0000, v48
	v_lshlrev_b32_e32 v48, 16, v49
	v_and_b32_e32 v49, 0xffff0000, v49
	v_lshlrev_b32_e32 v96, 16, v50
	v_and_b32_e32 v97, 0xffff0000, v50
	v_lshlrev_b32_e32 v50, 16, v51
	v_and_b32_e32 v51, 0xffff0000, v51
	v_pk_add_f32 v[38:39], v[38:39], v[96:97]
	v_pk_add_f32 v[48:49], v[48:49], v[50:51]
	v_pk_add_f32 v[50:51], v[94:95], v[38:39]
	v_pk_add_f32 v[48:49], v[36:37], v[48:49]
	s_nop 0
	s_waitcnt vmcnt(35)
	v_pk_mul_f32 v[38:39], v[106:107], 0.5 op_sel_hi:[1,0]
	v_pk_mul_f32 v[36:37], v[104:105], 0.5 op_sel_hi:[1,0]
	v_pk_mul_f32 v[38:39], v[38:39], v[48:49]
	v_pk_mul_f32 v[36:37], v[36:37], v[50:51]
	v_pk_fma_f32 v[30:31], v[30:31], s[4:5], v[38:39] op_sel_hi:[1,0,1]
	v_pk_fma_f32 v[28:29], v[28:29], s[4:5], v[36:37] op_sel_hi:[1,0,1]
	s_nop 0
	s_nop 0
	s_nop 0
	s_nop 0
	s_waitcnt vmcnt(34)
	v_lshlrev_b32_e32 v94, 16, v136
	v_and_b32_e32 v95, 0xffff0000, v136
	v_lshlrev_b32_e32 v36, 16, v137
	v_and_b32_e32 v37, 0xffff0000, v137
	s_waitcnt vmcnt(33)
	v_lshlrev_b32_e32 v96, 16, v138
	v_and_b32_e32 v97, 0xffff0000, v138
	v_lshlrev_b32_e32 v38, 16, v139
	v_and_b32_e32 v39, 0xffff0000, v139
	v_pk_add_f32 v[94:95], v[94:95], v[96:97]
	v_pk_add_f32 v[36:37], v[36:37], v[38:39]
	s_waitcnt vmcnt(32)
	v_lshlrev_b32_e32 v38, 16, v140
	v_and_b32_e32 v39, 0xffff0000, v140
	v_lshlrev_b32_e32 v48, 16, v141
	v_and_b32_e32 v49, 0xffff0000, v141
	s_waitcnt vmcnt(31)
;     ...
;         if (POST && part != nullptr && m >= ML) {
;             const v2u* pp = (const v2u*)(part + (size_t)(m - ML) * D);
; #pragma unroll
;             for (int j = 0; j < 8; ++j) { const int o = F.lane + 64 * j; const v2u p0 = pp[o], p1 = pp[o + (size_t)MC * D / 4], p2 = pp[o + 2 * ((size_t)MC * D / 4)], p3 = pp[o + 3 * ((size_t)MC * D / 4)];
;                 const f32x4 ps = ((f32x4){bflo(p0.x), bfhi(p0.x), bflo(p0.y), bfhi(p0.y)} + (f32x4){bflo(p1.x), bfhi(p1.x), bflo(p1.y), bfhi(p1.y)}) + ((f32x4){bflo(p2.x), bfhi(p2.x), bflo(p2.y), bfhi(p2.y)} + (f32x4){bflo(p3.x), bfhi(p3.x), bflo(p3.y), bfhi(p3.y)});
;                 v[j] = v[j] * ALPHA + ((const f32x4*)pmod)[o] * pcoef * ps; }
	v_lshlrev_b32_e32 v96, 16, v142
	v_and_b32_e32 v97, 0xffff0000, v142
	v_lshlrev_b32_e32 v50, 16, v143
	v_and_b32_e32 v51, 0xffff0000, v143
	v_pk_add_f32 v[38:39], v[38:39], v[96:97]
	v_pk_add_f32 v[48:49], v[48:49], v[50:51]
	v_pk_add_f32 v[50:51], v[94:95], v[38:39]
	v_pk_add_f32 v[48:49], v[36:37], v[48:49]
	s_nop 0
	s_waitcnt vmcnt(30)
	v_pk_mul_f32 v[38:39], v[110:111], 0.5 op_sel_hi:[1,0]
	v_pk_mul_f32 v[36:37], v[108:109], 0.5 op_sel_hi:[1,0]
	s_nop 0
	v_pk_mul_f32 v[50:51], v[36:37], v[50:51]
	v_pk_mul_f32 v[36:37], v[38:39], v[48:49]
	v_pk_fma_f32 v[38:39], v[32:33], s[4:5], v[50:51] op_sel_hi:[1,0,1]
	v_pk_fma_f32 v[36:37], v[34:35], s[4:5], v[36:37] op_sel_hi:[1,0,1]
	s_nop 0
	s_nop 0
	s_nop 0
	s_nop 0
	s_waitcnt vmcnt(29)
	v_lshlrev_b32_e32 v94, 16, v144
	v_and_b32_e32 v95, 0xffff0000, v144
	v_lshlrev_b32_e32 v32, 16, v145
	v_and_b32_e32 v33, 0xffff0000, v145
	s_waitcnt vmcnt(28)
	v_lshlrev_b32_e32 v96, 16, v146
	v_and_b32_e32 v97, 0xffff0000, v146
	v_lshlrev_b32_e32 v34, 16, v147
	v_and_b32_e32 v35, 0xffff0000, v147
	v_pk_add_f32 v[94:95], v[94:95], v[96:97]
	v_pk_add_f32 v[32:33], v[32:33], v[34:35]
	s_waitcnt vmcnt(27)
	v_lshlrev_b32_e32 v34, 16, v148
	v_and_b32_e32 v35, 0xffff0000, v148
	v_lshlrev_b32_e32 v48, 16, v149
	v_and_b32_e32 v49, 0xffff0000, v149
	s_waitcnt vmcnt(26)
	v_lshlrev_b32_e32 v96, 16, v150
	v_and_b32_e32 v97, 0xffff0000, v150
	v_lshlrev_b32_e32 v50, 16, v151
	v_and_b32_e32 v51, 0xffff0000, v151
	v_pk_add_f32 v[34:35], v[34:35], v[96:97]
	v_pk_add_f32 v[48:49], v[48:49], v[50:51]
	v_pk_add_f32 v[50:51], v[94:95], v[34:35]
	v_pk_add_f32 v[48:49], v[32:33], v[48:49]
	s_nop 0
	s_waitcnt vmcnt(25)
	v_pk_mul_f32 v[34:35], v[114:115], 0.5 op_sel_hi:[1,0]
	v_pk_mul_f32 v[32:33], v[112:113], 0.5 op_sel_hi:[1,0]
	v_pk_mul_f32 v[34:35], v[34:35], v[48:49]
	v_pk_mul_f32 v[32:33], v[32:33], v[50:51]
	v_pk_fma_f32 v[26:27], v[26:27], s[4:5], v[34:35] op_sel_hi:[1,0,1]
	v_pk_fma_f32 v[24:25], v[24:25], s[4:5], v[32:33] op_sel_hi:[1,0,1]
	s_nop 0
	s_nop 0
	s_nop 0
	s_nop 0
	s_waitcnt vmcnt(24)
	v_lshlrev_b32_e32 v94, 16, v152
	v_and_b32_e32 v95, 0xffff0000, v152
	v_lshlrev_b32_e32 v32, 16, v153
	v_and_b32_e32 v33, 0xffff0000, v153
	s_waitcnt vmcnt(23)
	v_lshlrev_b32_e32 v96, 16, v154
	v_and_b32_e32 v97, 0xffff0000, v154
	v_lshlrev_b32_e32 v34, 16, v155
	v_and_b32_e32 v35, 0xffff0000, v155
	v_pk_add_f32 v[94:95], v[94:95], v[96:97]
	v_pk_add_f32 v[32:33], v[32:33], v[34:35]
	s_waitcnt vmcnt(22)
	v_lshlrev_b32_e32 v34, 16, v156
	v_and_b32_e32 v35, 0xffff0000, v156
	v_lshlrev_b32_e32 v48, 16, v157
	v_and_b32_e32 v49, 0xffff0000, v157
	s_waitcnt vmcnt(21)
	v_lshlrev_b32_e32 v96, 16, v158
	v_and_b32_e32 v97, 0xffff0000, v158
	v_lshlrev_b32_e32 v50, 16, v159
	v_and_b32_e32 v51, 0xffff0000, v159
	v_pk_add_f32 v[34:35], v[34:35], v[96:97]
	v_pk_add_f32 v[48:49], v[48:49], v[50:51]
	v_pk_add_f32 v[50:51], v[94:95], v[34:35]
	v_pk_add_f32 v[48:49], v[32:33], v[48:49]
	s_nop 0
	s_waitcnt vmcnt(20)
	v_pk_mul_f32 v[34:35], v[118:119], 0.5 op_sel_hi:[1,0]
	v_pk_mul_f32 v[32:33], v[116:117], 0.5 op_sel_hi:[1,0]
	v_pk_mul_f32 v[34:35], v[34:35], v[48:49]
	v_pk_mul_f32 v[32:33], v[32:33], v[50:51]
	v_pk_fma_f32 v[22:23], v[22:23], s[4:5], v[34:35] op_sel_hi:[1,0,1]
	v_pk_fma_f32 v[20:21], v[20:21], s[4:5], v[32:33] op_sel_hi:[1,0,1]
	s_nop 0
	s_nop 0
	s_nop 0
	s_nop 0
	s_waitcnt vmcnt(19)
	v_lshlrev_b32_e32 v94, 16, v160
	v_and_b32_e32 v95, 0xffff0000, v160
	v_lshlrev_b32_e32 v32, 16, v161
	v_and_b32_e32 v33, 0xffff0000, v161
	s_waitcnt vmcnt(18)
	v_lshlrev_b32_e32 v96, 16, v162
	v_and_b32_e32 v97, 0xffff0000, v162
	v_lshlrev_b32_e32 v34, 16, v163
	v_and_b32_e32 v35, 0xffff0000, v163
	v_pk_add_f32 v[94:95], v[94:95], v[96:97]
	v_pk_add_f32 v[32:33], v[32:33], v[34:35]
	s_waitcnt vmcnt(17)
	v_lshlrev_b32_e32 v34, 16, v164
	v_and_b32_e32 v35, 0xffff0000, v164
	v_lshlrev_b32_e32 v48, 16, v165
	v_and_b32_e32 v49, 0xffff0000, v165
	s_waitcnt vmcnt(16)
	v_lshlrev_b32_e32 v96, 16, v166
	v_and_b32_e32 v97, 0xffff0000, v166
	v_lshlrev_b32_e32 v50, 16, v167
	v_and_b32_e32 v51, 0xffff0000, v167
	v_pk_add_f32 v[34:35], v[34:35], v[96:97]
	v_pk_add_f32 v[48:49], v[48:49], v[50:51]
	v_pk_add_f32 v[50:51], v[94:95], v[34:35]
	v_pk_add_f32 v[48:49], v[32:33], v[48:49]
	s_nop 0
	s_waitcnt vmcnt(15)
;     ...
;         if (POST && part != nullptr && m >= ML) {
;             const v2u* pp = (const v2u*)(part + (size_t)(m - ML) * D);
; #pragma unroll
;             for (int j = 0; j < 8; ++j) { const int o = F.lane + 64 * j; const v2u p0 = pp[o], p1 = pp[o + (size_t)MC * D / 4], p2 = pp[o + 2 * ((size_t)MC * D / 4)], p3 = pp[o + 3 * ((size_t)MC * D / 4)];
;                 const f32x4 ps = ((f32x4){bflo(p0.x), bfhi(p0.x), bflo(p0.y), bfhi(p0.y)} + (f32x4){bflo(p1.x), bfhi(p1.x), bflo(p1.y), bfhi(p1.y)}) + ((f32x4){bflo(p2.x), bfhi(p2.x), bflo(p2.y), bfhi(p2.y)} + (f32x4){bflo(p3.x), bfhi(p3.x), bflo(p3.y), bfhi(p3.y)});
;                 v[j] = v[j] * ALPHA + ((const f32x4*)pmod)[o] * pcoef * ps; }
	v_pk_mul_f32 v[34:35], v[122:123], 0.5 op_sel_hi:[1,0]
	v_pk_mul_f32 v[32:33], v[120:121], 0.5 op_sel_hi:[1,0]
	v_pk_mul_f32 v[34:35], v[34:35], v[48:49]
	v_pk_mul_f32 v[32:33], v[32:33], v[50:51]
	v_pk_fma_f32 v[18:19], v[18:19], s[4:5], v[34:35] op_sel_hi:[1,0,1]
	v_pk_fma_f32 v[16:17], v[16:17], s[4:5], v[32:33] op_sel_hi:[1,0,1]
	s_nop 0
	s_nop 0
	s_nop 0
	s_nop 0
	s_waitcnt vmcnt(14)
	v_lshlrev_b32_e32 v94, 16, v168
	v_and_b32_e32 v95, 0xffff0000, v168
	v_lshlrev_b32_e32 v32, 16, v169
	v_and_b32_e32 v33, 0xffff0000, v169
	s_waitcnt vmcnt(13)
	v_lshlrev_b32_e32 v96, 16, v170
	v_and_b32_e32 v97, 0xffff0000, v170
	v_lshlrev_b32_e32 v34, 16, v171
	v_and_b32_e32 v35, 0xffff0000, v171
	v_pk_add_f32 v[94:95], v[94:95], v[96:97]
	v_pk_add_f32 v[32:33], v[32:33], v[34:35]
	s_waitcnt vmcnt(12)
	v_lshlrev_b32_e32 v34, 16, v172
	v_and_b32_e32 v35, 0xffff0000, v172
	v_lshlrev_b32_e32 v48, 16, v173
	v_and_b32_e32 v49, 0xffff0000, v173
	s_waitcnt vmcnt(11)
	v_lshlrev_b32_e32 v96, 16, v174
	v_and_b32_e32 v97, 0xffff0000, v174
	v_lshlrev_b32_e32 v50, 16, v175
	v_and_b32_e32 v51, 0xffff0000, v175
	v_pk_add_f32 v[34:35], v[34:35], v[96:97]
	v_pk_add_f32 v[48:49], v[48:49], v[50:51]
	v_pk_add_f32 v[50:51], v[94:95], v[34:35]
	v_pk_add_f32 v[48:49], v[32:33], v[48:49]
	s_nop 0
	s_waitcnt vmcnt(10)
	v_pk_mul_f32 v[34:35], v[126:127], 0.5 op_sel_hi:[1,0]
	v_pk_mul_f32 v[32:33], v[124:125], 0.5 op_sel_hi:[1,0]
	v_pk_mul_f32 v[34:35], v[34:35], v[48:49]
	v_pk_mul_f32 v[32:33], v[32:33], v[50:51]
	v_pk_fma_f32 v[14:15], v[14:15], s[4:5], v[34:35] op_sel_hi:[1,0,1]
	v_pk_fma_f32 v[12:13], v[12:13], s[4:5], v[32:33] op_sel_hi:[1,0,1]
	s_nop 0
	s_nop 0
	s_nop 0
	s_nop 0
	s_waitcnt vmcnt(9)
	v_lshlrev_b32_e32 v94, 16, v176
	v_and_b32_e32 v95, 0xffff0000, v176
	v_lshlrev_b32_e32 v32, 16, v177
	v_and_b32_e32 v33, 0xffff0000, v177
	s_waitcnt vmcnt(8)
	v_lshlrev_b32_e32 v96, 16, v178
	v_and_b32_e32 v97, 0xffff0000, v178
	v_lshlrev_b32_e32 v34, 16, v179
	v_and_b32_e32 v35, 0xffff0000, v179
	v_pk_add_f32 v[94:95], v[94:95], v[96:97]
	v_pk_add_f32 v[32:33], v[32:33], v[34:35]
	s_waitcnt vmcnt(7)
	v_lshlrev_b32_e32 v34, 16, v180
	v_and_b32_e32 v35, 0xffff0000, v180
	v_lshlrev_b32_e32 v48, 16, v181
	v_and_b32_e32 v49, 0xffff0000, v181
	s_waitcnt vmcnt(6)
	v_lshlrev_b32_e32 v96, 16, v182
	v_and_b32_e32 v97, 0xffff0000, v182
	v_lshlrev_b32_e32 v50, 16, v183
	v_and_b32_e32 v51, 0xffff0000, v183
	v_pk_add_f32 v[34:35], v[34:35], v[96:97]
	v_pk_add_f32 v[48:49], v[48:49], v[50:51]
	v_pk_add_f32 v[50:51], v[94:95], v[34:35]
	v_pk_add_f32 v[48:49], v[32:33], v[48:49]
	s_nop 0
	s_waitcnt vmcnt(5)
	v_pk_mul_f32 v[34:35], v[130:131], 0.5 op_sel_hi:[1,0]
	v_pk_mul_f32 v[32:33], v[128:129], 0.5 op_sel_hi:[1,0]
	v_pk_mul_f32 v[34:35], v[34:35], v[48:49]
	v_pk_mul_f32 v[32:33], v[32:33], v[50:51]
	v_pk_fma_f32 v[10:11], v[10:11], s[4:5], v[34:35] op_sel_hi:[1,0,1]
	v_pk_fma_f32 v[8:9], v[8:9], s[4:5], v[32:33] op_sel_hi:[1,0,1]
	s_nop 0
	s_nop 0
	s_nop 0
	s_nop 0
	s_nop 0
	s_nop 0
	v_mov_b32_e32 v51, v30
	v_mov_b32_e32 v50, v36
	v_mov_b32_e32 v30, v37
	s_waitcnt vmcnt(4)
	v_lshlrev_b32_e32 v44, 16, v184
	v_and_b32_e32 v45, 0xffff0000, v184
	v_lshlrev_b32_e32 v32, 16, v185
	v_and_b32_e32 v33, 0xffff0000, v185
	s_waitcnt vmcnt(3)
	v_lshlrev_b32_e32 v46, 16, v186
	v_and_b32_e32 v47, 0xffff0000, v186
	v_lshlrev_b32_e32 v34, 16, v187
	v_and_b32_e32 v35, 0xffff0000, v187
	v_pk_add_f32 v[44:45], v[44:45], v[46:47]
	v_pk_add_f32 v[32:33], v[32:33], v[34:35]
	s_waitcnt vmcnt(2)
	v_lshlrev_b32_e32 v34, 16, v188
	v_and_b32_e32 v35, 0xffff0000, v188
	v_lshlrev_b32_e32 v42, 16, v189
	v_and_b32_e32 v43, 0xffff0000, v189
	s_waitcnt vmcnt(1)
	v_lshlrev_b32_e32 v46, 16, v190
	v_and_b32_e32 v47, 0xffff0000, v190
	v_lshlrev_b32_e32 v40, 16, v191
	v_and_b32_e32 v41, 0xffff0000, v191
	v_pk_add_f32 v[34:35], v[34:35], v[46:47]
	v_pk_add_f32 v[40:41], v[42:43], v[40:41]
	v_pk_add_f32 v[42:43], v[44:45], v[34:35]
	v_pk_add_f32 v[40:41], v[32:33], v[40:41]
	s_nop 0
	v_mov_b32_e32 v47, v28
	v_mov_b32_e32 v46, v38
	v_mov_b32_e32 v28, v39
	s_waitcnt vmcnt(0)
	v_pk_mul_f32 v[34:35], v[134:135], 0.5 op_sel_hi:[1,0]
	v_pk_mul_f32 v[32:33], v[132:133], 0.5 op_sel_hi:[1,0]
	v_pk_mul_f32 v[34:35], v[34:35], v[40:41]
	v_pk_mul_f32 v[32:33], v[32:33], v[42:43]
	v_pk_fma_f32 v[6:7], v[6:7], s[4:5], v[34:35] op_sel_hi:[1,0,1]
	v_pk_fma_f32 v[4:5], v[4:5], s[4:5], v[32:33] op_sel_hi:[1,0,1]
	s_branch .LBB0_409

;     ...
;         if (POST) {
;             float s = 0.f;
; #pragma unroll
;             for (int j = 0; j < 8; ++j) s += (v[j].x + v[j].y) + (v[j].z + v[j].w);
;             const float mean = wave_sum(s) * (1.f / D); float s2 = 0.f;
; #pragma unroll
;             for (int j = 0; j < 8; ++j) { v[j] = v[j] - mean; s2 += (v[j].x * v[j].x + v[j].y * v[j].y) + (v[j].z * v[j].z + v[j].w * v[j].w); }
;             const float rstd = 1.f / sqrtf(wave_sum(s2) * (1.f / D) + LN_EPS);
; #pragma unroll
;             for (int j = 0; j < 8; ++j) { const f32x4 gg = ((const f32x4*)g)[F.lane + 64 * j], bb = ((const f32x4*)b)[F.lane + 64 * j]; v[j] = v[j] * rstd * gg + bb; if (WX || m >= ML) ((f32x4*)xr)[F.lane + 64 * j] = v[j]; }
.LBB0_409:
	v_pk_add_f32 v[36:37], v[46:47], v[28:29]
	v_pk_add_f32 v[38:39], v[50:51], v[30:31]
	v_mov_b32_e32 v48, v25
	v_pk_add_f32 v[36:37], v[36:37], v[38:39]
	v_mov_b32_e32 v49, v26
	v_mov_b32_e32 v25, v27
	v_add_f32_e32 v3, 0, v37
	v_add_f32_e32 v43, v36, v3
	v_pk_add_f32 v[36:37], v[48:49], v[24:25]
	v_mov_b32_e32 v44, v17
	v_pk_add_f32 v[36:37], v[36:37], v[36:37] op_sel_hi:[0,1]
	v_mov_b32_e32 v42, v19
	v_add_f32_e32 v17, v20, v21
	v_add_f32_e32 v45, v22, v23
	v_mov_b32_e32 v19, v37
	v_mov_b32_e32 v40, v13
	v_mov_b32_e32 v41, v14
	v_mov_b32_e32 v13, v15
	v_pk_add_f32 v[38:39], v[16:17], v[44:45]
	v_pk_add_f32 v[36:37], v[18:19], v[42:43]
	v_mov_b32_e32 v32, v4
	v_pk_add_f32 v[36:37], v[38:39], v[36:37]
	v_pk_add_f32 v[38:39], v[40:41], v[12:13]
	v_pk_add_f32 v[36:37], v[36:37], v[36:37] op_sel_hi:[0,1]
	v_pk_add_f32 v[38:39], v[38:39], v[38:39] op_sel_hi:[0,1]
	v_mov_b32_e32 v34, v5
	v_mov_b32_e32 v14, v6
	v_mov_b32_e32 v26, v7
	v_add_f32_e32 v33, v8, v9
	v_add_f32_e32 v35, v10, v11
	v_mov_b32_e32 v15, v39
	v_mov_b32_e32 v27, v37
	v_pk_add_f32 v[32:33], v[32:33], v[34:35]
	v_pk_add_f32 v[14:15], v[14:15], v[26:27]
	s_nop 0
	v_pk_add_f32 v[14:15], v[32:33], v[14:15]
	global_load_dwordx4 v[32:35], v[60:61], off
	global_load_dwordx4 v[36:39], v[62:63], off
	global_load_dwordx4 v[160:163], v[60:61], off offset:1024
	global_load_dwordx4 v[164:167], v[62:63], off offset:1024
	global_load_dwordx4 v[168:171], v[60:61], off offset:2048
	global_load_dwordx4 v[172:175], v[62:63], off offset:2048
	global_load_dwordx4 v[176:179], v[60:61], off offset:3072
	global_load_dwordx4 v[180:183], v[62:63], off offset:3072
	global_load_dwordx4 v[184:187], v[64:65], off
	global_load_dwordx4 v[188:191], v[66:67], off
	global_load_dwordx4 v[196:199], v[68:69], off
	global_load_dwordx4 v[200:203], v[70:71], off
	global_load_dwordx4 v[204:207], v[72:73], off
	global_load_dwordx4 v[208:211], v[74:75], off
	global_load_dwordx4 v[212:215], v[76:77], off
	global_load_dwordx4 v[216:219], v[78:79], off
	v_add_f32_e32 v3, v14, v15
	v_mov_b32_e32 v14, v2
	s_nop 0
	v_add_f32_dpp v3, v3, v3 quad_perm:[1,0,3,2] row_mask:0xf bank_mask:0xf bound_ctrl:1
	s_nop 1
	v_add_f32_dpp v3, v3, v3 quad_perm:[2,3,0,1] row_mask:0xf bank_mask:0xf bound_ctrl:1
	s_nop 1
	v_add_f32_dpp v3, v3, v3 row_half_mirror row_mask:0xf bank_mask:0xf bound_ctrl:1
	s_nop 1
	v_add_f32_dpp v3, v3, v3 row_mirror row_mask:0xf bank_mask:0xf bound_ctrl:1
	s_nop 1
	v_mov_b32_dpp v14, v3 row_bcast:15 row_mask:0xa bank_mask:0xf
	v_add_f32_e32 v3, v3, v14
	v_mov_b32_e32 v14, v2
	s_nop 1
	v_mov_b32_dpp v14, v3 row_bcast:31 row_mask:0xc bank_mask:0xf
	v_add_f32_e32 v3, v3, v14
	s_nop 0
	v_readlane_b32 s19, v3, 63
	s_nop 1
	v_fmac_f32_e32 v31, s19, v224
	v_fmac_f32_e32 v29, s19, v224
	v_fmac_f32_e32 v51, s19, v224
	v_fmac_f32_e32 v47, s19, v224
	v_mul_f32_e32 v3, v29, v29
	v_mul_f32_e32 v14, v31, v31
	v_fmac_f32_e32 v3, v47, v47
	v_fmac_f32_e32 v14, v51, v51
	v_fmac_f32_e32 v30, s19, v224
	v_fmac_f32_e32 v28, s19, v224
	v_add_f32_e32 v3, v3, v14
	v_fmac_f32_e32 v50, s19, v224
	v_fmac_f32_e32 v46, s19, v224
	v_mul_f32_e32 v14, v28, v28
	v_mul_f32_e32 v15, v30, v30
	v_fmac_f32_e32 v14, v46, v46
	v_fmac_f32_e32 v15, v50, v50
	v_add_f32_e32 v14, v14, v15
	v_fmac_f32_e32 v25, s19, v224
	v_fmac_f32_e32 v48, s19, v224
	v_add_f32_e32 v3, v3, v14
	v_fmac_f32_e32 v49, s19, v224
	v_fmac_f32_e32 v24, s19, v224
	v_mul_f32_e32 v14, v48, v48
	v_mul_f32_e32 v15, v25, v25
	v_fmac_f32_e32 v14, v24, v24
	v_fmac_f32_e32 v15, v49, v49
	v_add_f32_e32 v14, v14, v15
	v_fmac_f32_e32 v23, s19, v224
	v_fmac_f32_e32 v21, s19, v224
	v_add_f32_e32 v3, v14, v3
	v_fmac_f32_e32 v22, s19, v224
	v_fmac_f32_e32 v20, s19, v224
	v_mul_f32_e32 v14, v21, v21
	v_mul_f32_e32 v15, v23, v23
	v_fmac_f32_e32 v14, v20, v20
	v_fmac_f32_e32 v15, v22, v22
	v_add_f32_e32 v14, v14, v15
	v_fmac_f32_e32 v42, s19, v224
	v_fmac_f32_e32 v44, s19, v224
	v_add_f32_e32 v3, v14, v3
	v_fmac_f32_e32 v18, s19, v224
	v_fmac_f32_e32 v16, s19, v224
	v_mul_f32_e32 v14, v44, v44
	v_mul_f32_e32 v15, v42, v42
	v_fmac_f32_e32 v14, v16, v16
	v_fmac_f32_e32 v15, v18, v18
	v_add_f32_e32 v14, v14, v15
	v_fmac_f32_e32 v13, s19, v224
	v_fmac_f32_e32 v40, s19, v224
	v_add_f32_e32 v3, v14, v3
	v_fmac_f32_e32 v41, s19, v224
	v_fmac_f32_e32 v12, s19, v224
	v_mul_f32_e32 v14, v40, v40
	v_mul_f32_e32 v15, v13, v13
	v_fmac_f32_e32 v14, v12, v12
	v_fmac_f32_e32 v15, v41, v41
	v_add_f32_e32 v14, v14, v15
	v_fmac_f32_e32 v11, s19, v224
	v_fmac_f32_e32 v9, s19, v224
	v_add_f32_e32 v3, v14, v3
	v_fmac_f32_e32 v10, s19, v224
	v_fmac_f32_e32 v8, s19, v224
	v_mul_f32_e32 v14, v9, v9
	v_mul_f32_e32 v15, v11, v11
	v_fma_f32 v95, s19, v224, v7
	v_fma_f32 v5, s19, v224, v5
	v_fmac_f32_e32 v14, v8, v8
	v_fmac_f32_e32 v15, v10, v10
	v_fma_f32 v94, s19, v224, v6
	v_fmac_f32_e32 v4, s19, v224
	v_mul_f32_e32 v6, v5, v5
	v_mul_f32_e32 v7, v95, v95
	v_add_f32_e32 v14, v14, v15
	v_fmac_f32_e32 v6, v4, v4
	v_fmac_f32_e32 v7, v94, v94
	v_add_f32_e32 v3, v14, v3
	v_add_f32_e32 v6, v6, v7
	v_add_f32_e32 v3, v6, v3
	v_mov_b32_e32 v6, v2
	s_nop 0
	v_add_f32_dpp v3, v3, v3 quad_perm:[1,0,3,2] row_mask:0xf bank_mask:0xf bound_ctrl:1
	s_nop 1
	v_add_f32_dpp v3, v3, v3 quad_perm:[2,3,0,1] row_mask:0xf bank_mask:0xf bound_ctrl:1
	s_nop 1
	v_add_f32_dpp v3, v3, v3 row_half_mirror row_mask:0xf bank_mask:0xf bound_ctrl:1
	s_nop 1
	v_add_f32_dpp v3, v3, v3 row_mirror row_mask:0xf bank_mask:0xf bound_ctrl:1
	s_nop 1
	v_mov_b32_dpp v6, v3 row_bcast:15 row_mask:0xa bank_mask:0xf
	v_add_f32_e32 v3, v3, v6
	v_mov_b32_e32 v6, v2
	s_nop 1
	v_mov_b32_dpp v6, v3 row_bcast:31 row_mask:0xc bank_mask:0xf
	v_add_f32_e32 v3, v3, v6
	s_nop 0
	v_readlane_b32 s4, v3, 63
	s_nop 1
	v_fma_f32 v3, s4, v226, v225
	v_cmp_gt_f32_e32 vcc, s73, v3
	v_mul_f32_e32 v6, 0x4f800000, v3
	s_nop 0
	v_cndmask_b32_e32 v3, v3, v6, vcc
	v_sqrt_f32_e32 v6, v3
	s_nop 0
	v_add_u32_e32 v7, -1, v6
	v_fma_f32 v14, -v7, v6, v3
	v_cmp_ge_f32_e64 s[4:5], 0, v14
	v_add_u32_e32 v14, 1, v6
	s_nop 0
	v_cndmask_b32_e64 v7, v6, v7, s[4:5]
	v_fma_f32 v6, -v14, v6, v3
	v_cmp_lt_f32_e64 s[4:5], 0, v6
	s_nop 1
	v_cndmask_b32_e64 v6, v7, v14, s[4:5]
	v_mul_f32_e32 v7, 0x37800000, v6
	v_cndmask_b32_e32 v6, v6, v7, vcc
	v_cmp_class_f32_e32 vcc, v3, v227
	s_nop 1
	v_cndmask_b32_e32 v3, v6, v3, vcc
	v_div_scale_f32 v6, s[4:5], v3, v3, 1.0
	v_rcp_f32_e32 v7, v6
	s_nop 0
	v_fma_f32 v14, -v6, v7, 1.0
	v_fmac_f32_e32 v7, v14, v7
	v_div_scale_f32 v14, vcc, 1.0, v3, 1.0
	v_mul_f32_e32 v15, v14, v7
	v_fma_f32 v17, -v6, v15, v14
	v_fmac_f32_e32 v15, v17, v7
	v_fma_f32 v6, -v6, v15, v14
	v_div_fmas_f32 v6, v6, v7, v15
	v_div_fixup_f32 v96, v6, v3, 1.0
	v_mov_b32_e32 v6, v47
	v_mov_b32_e32 v7, v29
	v_mov_b32_e32 v14, v51
	v_mov_b32_e32 v15, v31
	v_pk_mul_f32 v[6:7], v[6:7], v[96:97] op_sel_hi:[1,0]
	v_pk_mul_f32 v[14:15], v[14:15], v[96:97] op_sel_hi:[1,0]
	v_cndmask_b32_e64 v3, 0, 1, s[26:27]
	s_waitcnt vmcnt(0)
;     ...
;             const float rstd = 1.f / sqrtf(wave_sum(s2) * (1.f / D) + LN_EPS);
; #pragma unroll
;             for (int j = 0; j < 8; ++j) { const f32x4 gg = ((const f32x4*)g)[F.lane + 64 * j], bb = ((const f32x4*)b)[F.lane + 64 * j]; v[j] = v[j] * rstd * gg + bb; if (WX || m >= ML) ((f32x4*)xr)[F.lane + 64 * j] = v[j]; }
;             if (!WX && m < ML && F.lane == 0) *(v2f*)(WSP(float, WS_STATS) + 2 * m) = (v2f){mean, rstd};
	v_pk_fma_f32 v[34:35], v[34:35], v[14:15], v[38:39]
	v_pk_fma_f32 v[32:33], v[32:33], v[6:7], v[36:37]
	v_cmp_ne_u32_e64 s[4:5], 1, v3
	s_andn2_b64 vcc, exec, s[26:27]
	v_lshl_add_u64 v[6:7], v[0:1], 4, s[24:25]
	s_cbranch_vccnz .LBB0_411
	global_store_dwordx4 v[6:7], v[32:35], off
.LBB0_411:
	s_nop 0
	s_nop 0
	v_mov_b32_e32 v47, v28
	v_mov_b32_e32 v97, v96
	v_mov_b32_e32 v14, v96
	v_mov_b32_e32 v15, v96
	v_mov_b32_e32 v51, v30
	v_pk_mul_f32 v[26:27], v[50:51], v[14:15]
	v_pk_mul_f32 v[30:31], v[46:47], v[96:97]
	s_and_b64 vcc, exec, s[4:5]
	s_nop 0
	v_pk_fma_f32 v[28:29], v[26:27], v[162:163], v[166:167]
	v_pk_fma_f32 v[26:27], v[30:31], v[160:161], v[164:165]
	s_cbranch_vccnz .LBB0_413
	global_store_dwordx4 v[6:7], v[26:29], off offset:1024
.LBB0_413:
	s_nop 0
	s_nop 0
	v_mov_b32_e32 v30, v24
	v_mov_b32_e32 v31, v48
	v_mov_b32_e32 v24, v49
	v_pk_mul_f32 v[14:15], v[24:25], v[14:15]
	v_pk_mul_f32 v[24:25], v[30:31], v[96:97]
	s_and_b64 vcc, exec, s[4:5]
	s_nop 0
	v_pk_fma_f32 v[38:39], v[14:15], v[170:171], v[174:175]
	v_pk_fma_f32 v[36:37], v[24:25], v[168:169], v[172:173]
	s_cbranch_vccnz .LBB0_415
	global_store_dwordx4 v[6:7], v[36:39], off offset:2048
.LBB0_415:
	s_nop 0
	s_nop 0
	v_mov_b32_e32 v14, v96
	v_mov_b32_e32 v15, v96
	v_pk_mul_f32 v[20:21], v[20:21], v[96:97]
	v_pk_mul_f32 v[22:23], v[22:23], v[14:15]
	s_and_b64 vcc, exec, s[4:5]
	s_nop 0
	v_pk_fma_f32 v[22:23], v[22:23], v[178:179], v[182:183]
	v_pk_fma_f32 v[20:21], v[20:21], v[176:177], v[180:181]
	s_cbranch_vccnz .LBB0_417
	global_store_dwordx4 v[6:7], v[20:23], off offset:3072
.LBB0_417:
	v_mov_b32_e32 v17, v44
	s_nop 0
	s_nop 0
	v_mov_b32_e32 v19, v42
	v_pk_mul_f32 v[6:7], v[18:19], v[14:15]
	v_pk_mul_f32 v[14:15], v[16:17], v[96:97]
	s_and_b64 vcc, exec, s[4:5]
	s_nop 0
	v_pk_fma_f32 v[16:17], v[6:7], v[186:187], v[190:191]
	v_pk_fma_f32 v[14:15], v[14:15], v[184:185], v[188:189]
	s_cbranch_vccnz .LBB0_419
	v_lshl_add_u64 v[6:7], v[52:53], 4, s[24:25]
	global_store_dwordx4 v[6:7], v[14:17], off
.LBB0_419:
	s_nop 0
	s_nop 0
	v_mov_b32_e32 v18, v12
	v_mov_b32_e32 v19, v40
	v_mov_b32_e32 v6, v96
	v_mov_b32_e32 v7, v96
	v_mov_b32_e32 v12, v41
	v_pk_mul_f32 v[12:13], v[12:13], v[6:7]
	v_pk_mul_f32 v[18:19], v[18:19], v[96:97]
	s_and_b64 vcc, exec, s[4:5]
	s_nop 0
	v_pk_fma_f32 v[42:43], v[12:13], v[198:199], v[202:203]
	v_pk_fma_f32 v[40:41], v[18:19], v[196:197], v[200:201]
	s_cbranch_vccnz .LBB0_421
	v_lshl_add_u64 v[12:13], v[54:55], 4, s[24:25]
	global_store_dwordx4 v[12:13], v[40:43], off
.LBB0_421:
	s_nop 0
	s_nop 0
	v_pk_mul_f32 v[6:7], v[10:11], v[6:7]
	v_pk_mul_f32 v[10:11], v[8:9], v[96:97]
	s_and_b64 vcc, exec, s[4:5]
	s_nop 0
	v_pk_fma_f32 v[8:9], v[6:7], v[206:207], v[210:211]
	v_pk_fma_f32 v[6:7], v[10:11], v[204:205], v[208:209]
	s_cbranch_vccnz .LBB0_423
	v_lshl_add_u64 v[10:11], v[56:57], 4, s[24:25]
	global_store_dwordx4 v[10:11], v[6:9], off
.LBB0_423:
	s_nop 0
	s_nop 0
	s_nop 0
	v_mov_b32_e32 v18, v96
	v_mov_b32_e32 v19, v96
	v_pk_mul_f32 v[4:5], v[4:5], v[96:97]
	v_pk_mul_f32 v[18:19], v[94:95], v[18:19]
	s_and_b64 vcc, exec, s[4:5]
	s_nop 0
	v_pk_fma_f32 v[12:13], v[18:19], v[214:215], v[218:219]
	v_pk_fma_f32 v[10:11], v[4:5], v[212:213], v[216:217]
	s_cbranch_vccnz .LBB0_425
	v_lshl_add_u64 v[4:5], v[58:59], 4, s[24:25]
	global_store_dwordx4 v[4:5], v[10:13], off

;     __host__ __device__ bool next(int i, Unit& u) const {
;         const long L = (long)i * G + c; if (L >= nwg) return false;
;         int wgid = (int)L; { const int q = nwg / NXCD, r = nwg % NXCD, xcd = wgid % NXCD, off = wgid / NXCD; wgid = (xcd < r ? xcd * (q + 1) : r * (q + 1) + (xcd - r) * q) + off; }
; template <class Epi, class Sched, bool ALIGN_EPI = false, bool SP2 = false>
; __device__ __forceinline__ void gemm_phase(PG8_LAS unsigned char* lds, const Gemm g, const Sched& S, const Epi& E, int tid_in) {
;     ...
;     for (int i = 0; i < 2; ++i) { int R, C; stage_rc(tid * 16 + i * 8192, R, C); const int Rb = Epi::PERM ? ((R & ~31) + perm32(R & 31)) : R;
;         voffA[i] = (unsigned)(R * lda + C) * 2u; voffB[i] = (unsigned)(Rb * ldb + C) * 2u; }
;     const size_t kstep = (size_t)(BK * 2);
;     const size_t hsA = (size_t)HALF * lda * 2, hsB = (size_t)HALF * ldb * 2;
;     const size_t tsA = 2 * hsA, tsB = 2 * hsB;
;     const unsigned ldsw = (unsigned)wid * 1024u;
;     const int aoff = lds_byte(wr * 64 + fr, fq * 8), boff = lds_byte(wc * 32 + fr, fq * 8);
;     ...
;     Unit cur, nxt; int ui = 0;
;     if (!S.next(0, cur)) return;
;     f32x4 acc[2][2][4][2];
; #pragma unroll
;     for (int a = 0; a < 2; ++a)
; #pragma unroll
;         for (int b = 0; b < 2; ++b)
; #pragma unroll
;             for (int m = 0; m < 4; ++m)
; #pragma unroll
;                 for (int n = 0; n < 2; ++n) acc[a][b][m][n] = (f32x4){0.f, 0.f, 0.f, 0.f};
;     bf16x8 At[4][2], B0[2][2], B1[2][2];
;     const char* cA = (const char*)g.A + (size_t)cur.pm * tsA + (size_t)cur.kq * g.kqb; const char* cB = (const char*)g.Bt + (size_t)cur.pn * tsB + (size_t)cur.kq * g.kqb;
;     S.a_ready(cur);
;     if constexpr (SP2) {
;         PG8_STAGE(PG8_SB(0, 0), cB, voffB); PG8_STAGE(PG8_SB(0, 1), cB + hsB, voffB); PG8_STAGE(PG8_SA(0, 0), cA, voffA); PG8_STAGE(PG8_SA(0, 1), cA + hsA, voffA);
;         if (wr == 1) PG8_BAR;
;         PG8_WAIT_V(2); PG8_BAR;
;         PG8_STAGE(PG8_SB(1, 0), cB + kstep, voffB); PG8_STAGE(PG8_SA(1, 0), cA + kstep, voffA); PG8_STAGE(PG8_SB(1, 1), cB + hsB + kstep, voffB);
;         PG8_WAIT_V(6); PG8_BAR;
;     } else {
;         PG8_STAGE(PG8_SB(0, 0), cB, voffB); PG8_STAGE(PG8_SA(0, 0), cA, voffA); PG8_STAGE(PG8_SB(0, 1), cB + hsB, voffB); PG8_STAGE(PG8_SA(0, 1), cA + hsA, voffA);
;         if (wr == 1) PG8_BAR;
;         PG8_WAIT_V(4); PG8_BAR;
.LBB0_674:
	s_mov_b32 s0, s95
	v_mbcnt_lo_u32_b32 v0, -1, 0
	v_mbcnt_hi_u32_b32 v0, -1, v0
	s_mov_b32 s26, s92
	v_lshl_add_u32 v16, s0, 6, v0
	s_mov_b32 s27, s93
	s_sub_i32 s27, s93, 64
	s_cmp_lt_i32 s27, 0
	s_cselect_b32 s2, s92, 0
	s_add_i32 s27, s27, s2
	s_mov_b32 s2, s50
	s_mov_b64 s[4:5], s[90:91]
	s_mov_b64 s[0:1], s[88:89]
	s_mov_b64 s[0:1], s[86:87]
	s_movk_i32 s17, 0x100
	v_readfirstlane_b32 s20, v16
	s_movk_i32 s12, 0x100
	s_movk_i32 s18, 0x300
	s_mov_b32 s28, s67
	s_mov_b32 s29, s67
	s_cmpk_gt_i32 s27, 0x23f
	s_cbranch_scc1 .LBB0_695
	v_lshlrev_b32_e32 v1, 4, v16
	v_add_u32_e32 v0, 0x2000, v1
	v_ashrrev_i32_e32 v3, 31, v0
	v_lshrrev_b32_e32 v3, 22, v3
	v_add_u32_e32 v3, v0, v3
	v_ashrrev_i32_e32 v3, 10, v3
	v_mul_i32_i24_e32 v4, 0x400, v3
	v_sub_u32_e32 v0, v0, v4
	v_lshrrev_b32_e32 v4, 4, v0
	v_bitop3_b32 v0, v4, v0, 32 bitop3:0x6c
	v_ashrrev_i32_e32 v4, 31, v0
	v_lshrrev_b32_e32 v4, 26, v4
	v_add_u32_e32 v4, v0, v4
	v_lshlrev_b32_e32 v6, 3, v3
	v_ashrrev_i32_e32 v5, 6, v4
	v_and_b32_e32 v6, -16, v6
	v_lshlrev_b32_e32 v3, 5, v3
	v_add_u32_e32 v6, v5, v6
	v_and_b32_e32 v17, 32, v3
	v_and_b32_e32 v3, 0xc0, v4
	v_and_b32_e32 v5, 3, v5
	s_mov_b32 s3, 0x7fffffe0
	v_lshrrev_b32_e32 v7, 2, v6
	v_lshlrev_b32_e32 v8, 1, v6
	v_sub_u32_e32 v0, v0, v3
	v_and_or_b32 v5, v6, s3, v5
	v_and_b32_e32 v7, 4, v7
	v_and_b32_e32 v8, 24, v8
	v_ashrrev_i16_sdwa v0, v237, sext(v0) dst_sel:DWORD dst_unused:UNUSED_PAD src0_sel:DWORD src1_sel:BYTE_0
	v_or3_b32 v5, v5, v7, v8
	v_bfe_i32 v18, v0, 0, 16
	v_mul_lo_u32 v5, v5, s12
	v_add_u32_e32 v3, v17, v18
	v_mul_lo_u32 v19, v6, s18
	v_add_lshl_u32 v0, v5, v3, 1
	v_add_lshl_u32 v148, v3, v19, 1
	v_bfe_i32 v3, v16, 27, 1
	v_lshrrev_b32_e32 v3, 22, v3
	v_add_u32_e32 v3, v1, v3
	v_and_b32_e32 v3, 0xfffffc00, v3
	v_sub_u32_e32 v1, v1, v3
	v_lshrrev_b32_e32 v3, 4, v1
	v_ashrrev_i32_e32 v5, 31, v16
	v_bitop3_b32 v1, v3, v1, 32 bitop3:0x6c
	v_lshrrev_b32_e32 v5, 26, v5
	v_ashrrev_i32_e32 v3, 31, v1
	v_add_u32_e32 v5, v16, v5
	s_add_u32 s30, s4, 0x47100200
	v_lshrrev_b32_e32 v3, 26, v3
	v_ashrrev_i32_e32 v5, 6, v5
	s_addc_u32 s31, s5, 0
	v_add_u32_e32 v3, v1, v3
	v_lshlrev_b32_e32 v6, 3, v5
	s_add_u32 s33, s4, 0xba00000
	v_ashrrev_i32_e32 v4, 6, v3
	v_and_b32_e32 v6, -16, v6
	s_addc_u32 s34, s5, 0
	v_add_u32_e32 v6, v4, v6
	v_and_b32_e32 v4, 3, v4
	s_ashr_i32 s36, s27, 31
	v_and_or_b32 v4, v6, s3, v4
	s_lshr_b32 s3, s36, 29
	s_add_i32 s3, s27, s3
	s_ashr_i32 s21, s20, 6
	s_ashr_i32 s19, s18, 31
	s_ashr_i32 s13, s12, 31
	s_ashr_i32 s16, s3, 3
	s_and_b32 s3, s3, -8
	s_load_dwordx2 s[14:15], s[0:1], 0x78
	s_ashr_i32 s47, s20, 8
	s_lshl_b64 s[0:1], s[18:19], 8
	s_lshl_b64 s[6:7], s[12:13], 8
	s_lshl_b64 s[8:9], s[18:19], 9
	s_lshl_b64 s[10:11], s[12:13], 9
	s_lshl_b32 s35, s21, 10
	s_sub_i32 s3, s27, s3
	s_cmp_lt_i32 s3, 0
	s_movk_i32 s22, 0x49
	s_cselect_b32 s22, s22, 0x48
	s_mul_i32 s3, s22, s3
	s_add_i32 s3, s3, s16
	s_ashr_i32 s16, s3, 31
	s_lshr_b32 s16, s16, 26
	s_add_i32 s16, s3, s16
	s_ashr_i32 s22, s16, 6
	s_and_b32 s16, s16, 0xffc0
	s_sub_i32 s3, s3, s16
	s_bfe_i32 s16, s3, 0x80000
	s_bfe_u32 s16, s16, 0x3000c
	s_add_i32 s23, s3, s16
	s_bfe_i32 s16, s23, 0x80000
	s_and_b32 s23, s23, 0xf8
	s_sub_i32 s3, s3, s23
	s_lshl_b32 s22, s22, 3
	s_sext_i32_i8 s3, s3
	s_add_i32 s51, s22, s3
	s_ashr_i32 s3, s51, 31
	v_mul_lo_u32 v22, v6, s18
	s_sext_i32_i16 s24, s16
	s_mul_i32 s3, s8, s3
	s_mul_hi_u32 s22, s8, s51
	s_lshr_b64 s[18:19], s[18:19], 23
	v_lshrrev_b32_e32 v7, 2, v6
	v_lshlrev_b32_e32 v8, 1, v6
	s_lshr_b32 s16, s24, 3
	s_add_i32 s3, s22, s3
	s_mul_i32 s18, s18, s51
	v_and_b32_e32 v7, 4, v7
	v_and_b32_e32 v8, 24, v8
	s_add_i32 s3, s3, s18
	s_bfe_i64 s[18:19], s[16:17], 0x100000
	v_or3_b32 v4, v4, v7, v8
	s_ashr_i32 s18, s24, 3
	v_mul_lo_u32 v4, v4, s12
	v_and_b32_e32 v3, 0xc0, v3
	s_mul_hi_u32 s22, s10, s18
	s_mul_i32 s19, s10, s19
	s_lshr_b64 s[12:13], s[12:13], 23
	v_sub_u32_e32 v1, v1, v3
	s_add_i32 s19, s22, s19
	s_mul_i32 s12, s12, s18
	v_lshlrev_b32_e32 v5, 5, v5
	v_ashrrev_i16_sdwa v1, v237, sext(v1) dst_sel:DWORD dst_unused:UNUSED_PAD src0_sel:DWORD src1_sel:BYTE_0
	s_add_i32 s19, s19, s12
	s_mul_i32 s12, s10, s18
	v_and_b32_e32 v20, 32, v5
	v_bfe_i32 v21, v1, 0, 16
	s_add_u32 s22, s33, s12
	v_add_u32_e32 v1, v20, v21
	s_addc_u32 s23, s34, s19
	s_add_i32 s37, s35, 0
	v_add_lshl_u32 v150, v4, v1, 1
	s_add_i32 m0, s37, 0x10000
	s_mul_i32 s25, s8, s51
	global_load_lds_dwordx4 v150, s[22:23]
	s_add_i32 m0, s37, 0x12000
	s_add_u32 s12, s22, s6
	global_load_lds_dwordx4 v0, s[22:23]
	s_addc_u32 s13, s23, s7
	s_add_i32 m0, s37, 0x14000
	v_add_lshl_u32 v152, v1, v22, 1
	global_load_lds_dwordx4 v150, s[12:13]
	s_add_i32 m0, s37, 0x16000
	s_add_u32 s24, s30, s25
	v_mov_b32_e32 v151, v2
	v_mov_b32_e32 v1, v2
	s_addc_u32 s25, s31, s3
	s_add_i32 s38, s37, 0x2000
	v_lshl_add_u64 v[8:9], s[12:13], 0, v[150:151]
	v_lshl_add_u64 v[10:11], s[12:13], 0, v[0:1]
	global_load_lds_dwordx4 v0, s[12:13]
	s_mov_b32 m0, s37
	s_add_u32 s12, s24, s0
	global_load_lds_dwordx4 v152, s[24:25]
	s_mov_b32 m0, s38
	s_addc_u32 s13, s25, s1
	s_add_i32 s39, s37, 0x4000
	global_load_lds_dwordx4 v148, s[24:25]
	s_mov_b32 m0, s39
	s_add_i32 s40, s37, 0x6000
	global_load_lds_dwordx4 v152, s[12:13]
	s_mov_b32 m0, s40
	v_mov_b32_e32 v153, v2
	global_load_lds_dwordx4 v148, s[12:13]
	v_mov_b32_e32 v149, v2
	s_cmp_eq_u32 s47, 1
	v_lshl_add_u64 v[4:5], s[22:23], 0, v[150:151]
	v_lshl_add_u64 v[6:7], s[22:23], 0, v[0:1]
	v_lshl_add_u64 v[12:13], s[24:25], 0, v[152:153]
	v_lshl_add_u64 v[14:15], s[24:25], 0, v[148:149]
	s_cselect_b64 s[12:13], -1, 0
	s_cmp_lg_u32 s47, 1
	s_cbranch_scc1 .LBB0_677
	s_barrier

;     __host__ __device__ bool next(int i, Unit& u) const {
;         const long L = (long)i * G + c; if (L >= nwg) return false;
;         int wgid = (int)L; { const int q = nwg / NXCD, r = nwg % NXCD, xcd = wgid % NXCD, off = wgid / NXCD; wgid = (xcd < r ? xcd * (q + 1) : r * (q + 1) + (xcd - r) * q) + off; }
; template <class Epi, class Sched, bool ALIGN_EPI = false, bool SP2 = false>
; __device__ __forceinline__ void gemm_phase(PG8_LAS unsigned char* lds, const Gemm g, const Sched& S, const Epi& E, int tid_in) {
;     ...
;     for (int i = 0; i < 2; ++i) { int R, C; stage_rc(tid * 16 + i * 8192, R, C); const int Rb = Epi::PERM ? ((R & ~31) + perm32(R & 31)) : R;
;         voffA[i] = (unsigned)(R * lda + C) * 2u; voffB[i] = (unsigned)(Rb * ldb + C) * 2u; }
;     const size_t kstep = (size_t)(BK * 2);
;     const size_t hsA = (size_t)HALF * lda * 2, hsB = (size_t)HALF * ldb * 2;
;     const size_t tsA = 2 * hsA, tsB = 2 * hsB;
;     const unsigned ldsw = (unsigned)wid * 1024u;
;     const int aoff = lds_byte(wr * 64 + fr, fq * 8), boff = lds_byte(wc * 32 + fr, fq * 8);
;     ...
;     Unit cur, nxt; int ui = 0;
;     if (!S.next(0, cur)) return;
;     f32x4 acc[2][2][4][2];
; #pragma unroll
;     for (int a = 0; a < 2; ++a)
; #pragma unroll
;         for (int b = 0; b < 2; ++b)
; #pragma unroll
;             for (int m = 0; m < 4; ++m)
; #pragma unroll
;                 for (int n = 0; n < 2; ++n) acc[a][b][m][n] = (f32x4){0.f, 0.f, 0.f, 0.f};
;     bf16x8 At[4][2], B0[2][2], B1[2][2];
;     const char* cA = (const char*)g.A + (size_t)cur.pm * tsA + (size_t)cur.kq * g.kqb; const char* cB = (const char*)g.Bt + (size_t)cur.pn * tsB + (size_t)cur.kq * g.kqb;
;     S.a_ready(cur);
;     if constexpr (SP2) {
;         PG8_STAGE(PG8_SB(0, 0), cB, voffB); PG8_STAGE(PG8_SB(0, 1), cB + hsB, voffB); PG8_STAGE(PG8_SA(0, 0), cA, voffA); PG8_STAGE(PG8_SA(0, 1), cA + hsA, voffA);
;         if (wr == 1) PG8_BAR;
;         PG8_WAIT_V(2); PG8_BAR;
;         PG8_STAGE(PG8_SB(1, 0), cB + kstep, voffB); PG8_STAGE(PG8_SA(1, 0), cA + kstep, voffA); PG8_STAGE(PG8_SB(1, 1), cB + hsB + kstep, voffB);
;         PG8_WAIT_V(6); PG8_BAR;
;     } else {
;         PG8_STAGE(PG8_SB(0, 0), cB, voffB); PG8_STAGE(PG8_SA(0, 0), cA, voffA); PG8_STAGE(PG8_SB(0, 1), cB + hsB, voffB); PG8_STAGE(PG8_SA(0, 1), cA + hsA, voffA);
;         if (wr == 1) PG8_BAR;
;         PG8_WAIT_V(4); PG8_BAR;
.LBB0_695:
	s_mov_b32 s0, s95
	v_mbcnt_lo_u32_b32 v0, -1, 0
	v_mbcnt_hi_u32_b32 v0, -1, v0
	s_mov_b32 s26, s92
	v_lshl_add_u32 v16, s0, 6, v0
	s_mov_b32 s27, s93
	s_sub_i32 s27, s93, 128
	s_cmp_lt_i32 s27, 0
	s_cselect_b32 s0, s92, 0
	s_add_i32 s27, s27, s0
	s_mov_b32 s0, s50
	s_mov_b64 s[0:1], s[88:89]
	s_mov_b64 s[2:3], s[90:91]
	s_mov_b64 s[0:1], s[86:87]
	s_movk_i32 s16, 0x100
	v_readfirstlane_b32 s5, v16
	s_movk_i32 s12, 0x100
	s_movk_i32 s14, 0x300
	s_mov_b32 s28, s67
	s_mov_b32 s29, s67
	s_cmpk_gt_i32 s27, 0x11f
	s_cbranch_scc1 .LBB0_716
	v_lshlrev_b32_e32 v1, 4, v16
	v_add_u32_e32 v0, 0x2000, v1
	v_ashrrev_i32_e32 v3, 31, v0
	v_lshrrev_b32_e32 v3, 22, v3
	v_add_u32_e32 v3, v0, v3
	v_ashrrev_i32_e32 v3, 10, v3
	v_mul_i32_i24_e32 v4, 0x400, v3
	v_sub_u32_e32 v0, v0, v4
	v_lshrrev_b32_e32 v4, 4, v0
	v_bitop3_b32 v0, v4, v0, 32 bitop3:0x6c
	v_ashrrev_i32_e32 v4, 31, v0
	v_lshrrev_b32_e32 v4, 26, v4
	v_add_u32_e32 v4, v0, v4
	v_lshlrev_b32_e32 v6, 3, v3
	v_ashrrev_i32_e32 v5, 6, v4
	v_and_b32_e32 v6, -16, v6
	v_lshlrev_b32_e32 v3, 5, v3
	v_add_u32_e32 v6, v5, v6
	v_and_b32_e32 v17, 32, v3
	v_and_b32_e32 v3, 0xc0, v4
	v_and_b32_e32 v5, 3, v5
	s_mov_b32 s4, 0x7fffffe0
	v_lshrrev_b32_e32 v7, 2, v6
	v_lshlrev_b32_e32 v8, 1, v6
	v_sub_u32_e32 v0, v0, v3
	v_and_or_b32 v5, v6, s4, v5
	v_and_b32_e32 v7, 4, v7
	v_and_b32_e32 v8, 24, v8
	v_ashrrev_i16_sdwa v0, v237, sext(v0) dst_sel:DWORD dst_unused:UNUSED_PAD src0_sel:DWORD src1_sel:BYTE_0
	v_or3_b32 v5, v5, v7, v8
	v_bfe_i32 v18, v0, 0, 16
	v_mul_lo_u32 v5, v5, s12
	v_add_u32_e32 v3, v17, v18
	v_mul_lo_u32 v19, v6, s14
	v_add_lshl_u32 v0, v5, v3, 1
	v_add_lshl_u32 v132, v3, v19, 1
	v_bfe_i32 v3, v16, 27, 1
	v_lshrrev_b32_e32 v3, 22, v3
	v_add_u32_e32 v3, v1, v3
	v_and_b32_e32 v3, 0xfffffc00, v3
	v_sub_u32_e32 v1, v1, v3
	v_lshrrev_b32_e32 v3, 4, v1
	v_ashrrev_i32_e32 v5, 31, v16
	v_bitop3_b32 v1, v3, v1, 32 bitop3:0x6c
	v_lshrrev_b32_e32 v5, 26, v5
	v_ashrrev_i32_e32 v3, 31, v1
	v_add_u32_e32 v5, v16, v5
	s_add_u32 s30, s2, 0x47100400
	v_lshrrev_b32_e32 v3, 26, v3
	v_ashrrev_i32_e32 v5, 6, v5
	s_addc_u32 s31, s3, 0
	v_add_u32_e32 v3, v1, v3
	v_lshlrev_b32_e32 v6, 3, v5
	s_add_u32 s33, s2, 0xbb00000
	v_ashrrev_i32_e32 v4, 6, v3
	v_and_b32_e32 v6, -16, v6
	s_addc_u32 s34, s3, 0
	v_add_u32_e32 v6, v4, v6
	v_and_b32_e32 v4, 3, v4
	s_ashr_i32 s36, s27, 31
	v_and_or_b32 v4, v6, s4, v4
	s_lshr_b32 s4, s36, 29
	s_add_i32 s4, s27, s4
	s_ashr_i32 s17, s5, 6
	s_ashr_i32 s15, s14, 31
	s_ashr_i32 s13, s12, 31
	s_ashr_i32 s19, s4, 3
	s_and_b32 s4, s4, -8
	s_ashr_i32 s18, s5, 8
	s_lshl_b64 s[0:1], s[14:15], 8
	s_lshl_b64 s[6:7], s[12:13], 8
	s_lshl_b64 s[8:9], s[14:15], 9
	s_lshl_b64 s[10:11], s[12:13], 9
	s_lshl_b32 s35, s17, 10
	s_sub_i32 s4, s27, s4
	s_cmp_lt_i32 s4, 0
	s_cselect_b32 s20, 37, 36
	s_mul_i32 s4, s20, s4
	s_add_i32 s4, s4, s19
	s_ashr_i32 s19, s4, 31
	s_lshr_b32 s19, s19, 27
	s_add_i32 s19, s4, s19
	s_ashr_i32 s20, s19, 5
	s_and_b32 s19, s19, 0xffe0
	s_sub_i32 s19, s4, s19
	s_bfe_i32 s4, s19, 0x80000
	s_bfe_u32 s4, s4, 0x3000c
	s_add_i32 s21, s19, s4
	s_bfe_i32 s4, s21, 0x80000
	s_and_b32 s21, s21, 0xf8
	s_sub_i32 s19, s19, s21
	s_lshl_b32 s20, s20, 3
	s_sext_i32_i8 s19, s19
	s_add_i32 s45, s20, s19
	s_ashr_i32 s19, s45, 31
	v_mul_lo_u32 v22, v6, s14
	s_sext_i32_i16 s22, s4
	s_mul_i32 s19, s8, s19
	s_mul_hi_u32 s20, s8, s45
	s_lshr_b64 s[14:15], s[14:15], 23
	v_lshrrev_b32_e32 v7, 2, v6
	v_lshlrev_b32_e32 v8, 1, v6
	s_lshr_b32 s4, s22, 3
	s_add_i32 s19, s20, s19
	s_mul_i32 s14, s14, s45
	v_and_b32_e32 v7, 4, v7
	v_and_b32_e32 v8, 24, v8
	s_add_i32 s19, s19, s14
	s_bfe_i64 s[14:15], s[4:5], 0x100000
	v_or3_b32 v4, v4, v7, v8
	s_ashr_i32 s14, s22, 3
	v_mul_lo_u32 v4, v4, s12
	v_and_b32_e32 v3, 0xc0, v3
	s_mul_hi_u32 s21, s10, s14
	s_mul_i32 s15, s10, s15
	s_lshr_b64 s[12:13], s[12:13], 23
	v_sub_u32_e32 v1, v1, v3
	s_add_i32 s15, s21, s15
	s_mul_i32 s12, s12, s14
	v_lshlrev_b32_e32 v5, 5, v5
	v_ashrrev_i16_sdwa v1, v237, sext(v1) dst_sel:DWORD dst_unused:UNUSED_PAD src0_sel:DWORD src1_sel:BYTE_0
	s_add_i32 s15, s15, s12
	s_mul_i32 s12, s10, s14
	v_and_b32_e32 v20, 32, v5
	v_bfe_i32 v21, v1, 0, 16
	s_add_u32 s22, s33, s12
	v_add_u32_e32 v1, v20, v21
	s_addc_u32 s23, s34, s15
	s_add_i32 s37, s35, 0
	v_add_lshl_u32 v134, v4, v1, 1
	s_add_i32 m0, s37, 0x10000
	s_mul_i32 s20, s8, s45
	global_load_lds_dwordx4 v134, s[22:23]
	s_add_i32 m0, s37, 0x12000
	s_add_u32 s12, s22, s6
	global_load_lds_dwordx4 v0, s[22:23]
	s_addc_u32 s13, s23, s7
	s_add_i32 m0, s37, 0x14000
	v_add_lshl_u32 v136, v1, v22, 1
	global_load_lds_dwordx4 v134, s[12:13]
	s_add_i32 m0, s37, 0x16000
	s_add_u32 s24, s30, s20
	v_mov_b32_e32 v135, v2
	v_mov_b32_e32 v1, v2
	s_addc_u32 s25, s31, s19
	s_add_i32 s38, s37, 0x2000
	v_lshl_add_u64 v[8:9], s[12:13], 0, v[134:135]
	v_lshl_add_u64 v[10:11], s[12:13], 0, v[0:1]
	global_load_lds_dwordx4 v0, s[12:13]
	s_mov_b32 m0, s37
	s_add_u32 s12, s24, s0
	global_load_lds_dwordx4 v136, s[24:25]
	s_mov_b32 m0, s38
	s_addc_u32 s13, s25, s1
	s_add_i32 s39, s37, 0x4000
	global_load_lds_dwordx4 v132, s[24:25]
	s_mov_b32 m0, s39
	s_add_i32 s40, s37, 0x6000
	global_load_lds_dwordx4 v136, s[12:13]
	s_mov_b32 m0, s40
	v_mov_b32_e32 v137, v2
	global_load_lds_dwordx4 v132, s[12:13]
	v_mov_b32_e32 v133, v2
	s_cmp_eq_u32 s18, 1
	v_lshl_add_u64 v[4:5], s[22:23], 0, v[134:135]
	v_lshl_add_u64 v[6:7], s[22:23], 0, v[0:1]
	v_lshl_add_u64 v[12:13], s[24:25], 0, v[136:137]
	v_lshl_add_u64 v[14:15], s[24:25], 0, v[132:133]
	s_cselect_b64 s[12:13], -1, 0
	s_cmp_lg_u32 s18, 1
	s_cbranch_scc1 .LBB0_698
	s_barrier

; __device__ __forceinline__ float* xrow(const Frame& F, int m) { return m < ML ? (float*)(F.out + (size_t)m * D) : WSP(float, WS_XC) + (size_t)(m - ML) * D; }
;     const int gw = F.bid * NWAVES + F.wave, NGW = F.G * NWAVES;
;     bf16* HB = WSP(bf16, WS_HB);
;     for (int m = gw; m < nrows; m += NGW) {
;         float* xr = xrow(F, m);
;         const float* xs = (m < ML) ? (src_l ? src_l + (size_t)m * D : xr) : (src_c ? src_c + (size_t)(m - ML) * D : xr);
;         f32x4 v[8];
; #pragma unroll
;         for (int j = 0; j < 8; ++j) v[j] = ((const f32x4*)xs)[F.lane + 64 * j];
;         if (POST && part != nullptr && m >= ML) {
;             const v2u* pp = (const v2u*)(part + (size_t)(m - ML) * D);
; #pragma unroll
;             for (int j = 0; j < 8; ++j) { const int o = F.lane + 64 * j; const v2u p0 = pp[o], p1 = pp[o + (size_t)MC * D / 4], p2 = pp[o + 2 * ((size_t)MC * D / 4)], p3 = pp[o + 3 * ((size_t)MC * D / 4)];
;                 const f32x4 ps = ((f32x4){bflo(p0.x), bfhi(p0.x), bflo(p0.y), bfhi(p0.y)} + (f32x4){bflo(p1.x), bfhi(p1.x), bflo(p1.y), bfhi(p1.y)}) + ((f32x4){bflo(p2.x), bfhi(p2.x), bflo(p2.y), bfhi(p2.y)} + (f32x4){bflo(p3.x), bfhi(p3.x), bflo(p3.y), bfhi(p3.y)});
;                 v[j] = v[j] * ALPHA + ((const f32x4*)pmod)[o] * pcoef * ps; }
;         }
;         if (POST) {
;             float s = 0.f;
; #pragma unroll
;             for (int j = 0; j < 8; ++j) s += (v[j].x + v[j].y) + (v[j].z + v[j].w);
;             const float mean = wave_sum(s) * (1.f / D); float s2 = 0.f;
; #pragma unroll
;             for (int j = 0; j < 8; ++j) { v[j] = v[j] - mean; s2 += (v[j].x * v[j].x + v[j].y * v[j].y) + (v[j].z * v[j].z + v[j].w * v[j].w); }
;             const float rstd = 1.f / sqrtf(wave_sum(s2) * (1.f / D) + LN_EPS);
; #pragma unroll
;             for (int j = 0; j < 8; ++j) { const f32x4 gg = ((const f32x4*)g)[F.lane + 64 * j], bb = ((const f32x4*)b)[F.lane + 64 * j]; v[j] = v[j] * rstd * gg + bb; if (WX || m >= ML) ((f32x4*)xr)[F.lane + 64 * j] = v[j]; }
.LBB0_1412:
	s_mov_b32 s0, 1
	s_mov_b64 s[2:3], s[90:91]
	v_mbcnt_lo_u32_b32 v0, -1, 0
	v_mbcnt_hi_u32_b32 v0, -1, v0
	s_lshl_b32 s1, s93, 3
	s_add_i32 s2, s1, s95
	s_cmpk_gt_i32 s2, 0x3fff
	s_cbranch_scc1 .LBB0_1415
	s_load_dwordx4 s[8:11], s[86:87], 0x30
	s_lshl_b32 s4, s92, 3
	s_mul_i32 s5, s0, 0x6000
	s_mul_hi_i32 s3, s0, 0x6000
	v_ashrrev_i32_e32 v1, 31, v0
	s_waitcnt lgkmcnt(0)
	s_add_u32 s0, s10, s5
	s_addc_u32 s1, s11, s3
	s_add_u32 s6, s8, s5
	s_addc_u32 s7, s9, s3
	v_lshlrev_b64 v[0:1], 4, v[0:1]
	s_lshl_b32 s20, s95, 13
	s_add_i32 s21, s20, 0x1000
	v_add_u32_e32 v86, s20, v0
	v_lshl_add_u64 v[2:3], s[6:7], 0, v[0:1]
	v_lshl_add_u64 v[4:5], s[0:1], 0, v[0:1]
	s_mov_b64 s[0:1], 0x5000
	v_lshl_add_u64 v[36:37], v[2:3], 0, s[0:1]
	v_lshl_add_u64 v[38:39], v[4:5], 0, s[0:1]
	s_mov_b64 s[0:1], 0x5400
	v_lshl_add_u64 v[40:41], v[2:3], 0, s[0:1]
	v_lshl_add_u64 v[42:43], v[4:5], 0, s[0:1]
	s_mov_b64 s[0:1], 0x5800
	v_lshl_add_u64 v[44:45], v[2:3], 0, s[0:1]
	v_lshl_add_u64 v[46:47], v[4:5], 0, s[0:1]
	s_mov_b64 s[0:1], 0x5c00
	s_ashr_i32 s3, s2, 31
	v_lshl_add_u64 v[48:49], v[2:3], 0, s[0:1]
	v_lshl_add_u64 v[50:51], v[4:5], 0, s[0:1]
	s_lshl_b64 s[0:1], s[2:3], 13
	s_add_u32 s0, s88, s0
	s_addc_u32 s1, s89, s1
	s_mov_b64 s[6:7], 0x4000
	v_lshl_add_u64 v[0:1], s[0:1], 0, v[0:1]
	s_mov_b64 s[0:1], 0x1000
	s_ashr_i32 s5, s4, 31
	v_lshl_add_u64 v[32:33], v[2:3], 0, s[6:7]
	v_lshl_add_u64 v[34:35], v[4:5], 0, s[6:7]
	v_lshl_add_u64 v[52:53], v[0:1], 0, s[0:1]
	v_mov_b64_e32 v[88:89], v[0:1]
	v_mov_b64_e32 v[90:91], v[52:53]
	s_lshl_b64 s[6:7], s[4:5], 13
	v_mov_b32_e32 v54, 0xba000000
	v_mov_b32_e32 v55, 0x3727c5ac
	v_mov_b32_e32 v56, 0x3a000000
	s_mov_b32 s3, 0xf800000
	v_mov_b32_e32 v57, 0x260
	global_load_dwordx4 v[96:99], v[32:33], off
	global_load_dwordx4 v[100:103], v[34:35], off
	global_load_dwordx4 v[104:107], v[32:33], off offset:1024
	global_load_dwordx4 v[108:111], v[34:35], off offset:1024
	global_load_dwordx4 v[112:115], v[32:33], off offset:2048
	global_load_dwordx4 v[116:119], v[34:35], off offset:2048
	global_load_dwordx4 v[120:123], v[32:33], off offset:3072
	global_load_dwordx4 v[124:127], v[34:35], off offset:3072
	global_load_dwordx4 v[128:131], v[36:37], off
	global_load_dwordx4 v[132:135], v[38:39], off
	global_load_dwordx4 v[136:139], v[40:41], off
	global_load_dwordx4 v[140:143], v[42:43], off
	global_load_dwordx4 v[144:147], v[44:45], off
	global_load_dwordx4 v[148:151], v[46:47], off
	global_load_dwordx4 v[152:155], v[48:49], off
	global_load_dwordx4 v[156:159], v[50:51], off
	s_mov_b32 m0, s20
	s_nop 0
	global_load_lds_dwordx4 v[88:89], off
	global_load_lds_dwordx4 v[88:89], off offset:1024
	global_load_lds_dwordx4 v[88:89], off offset:2048
	global_load_lds_dwordx4 v[88:89], off offset:3072
	s_mov_b32 m0, s21
	s_nop 0
	global_load_lds_dwordx4 v[90:91], off
	global_load_lds_dwordx4 v[90:91], off offset:1024
	global_load_lds_dwordx4 v[90:91], off offset:2048
	global_load_lds_dwordx4 v[90:91], off offset:3072
	v_lshl_add_u64 v[88:89], v[88:89], 0, s[6:7]
	v_lshl_add_u64 v[90:91], v[90:91], 0, s[6:7]
	s_waitcnt vmcnt(0)
.LBB0_1414:
	s_waitcnt vmcnt(8)
	ds_read_b128 v[28:31], v86
	ds_read_b128 v[24:27], v86 offset:1024
	ds_read_b128 v[20:23], v86 offset:2048
	ds_read_b128 v[16:19], v86 offset:3072
	ds_read_b128 v[12:15], v86 offset:4096
	ds_read_b128 v[8:11], v86 offset:5120
	ds_read_b128 v[4:7], v86 offset:6144
	ds_read_b128 v[0:3], v86 offset:7168
	v_mov_b32_e32 v84, 0
	v_mov_b32_e32 v85, 0
	s_add_i32 s2, s2, s4
	s_cmpk_lt_i32 s2, 0x4000
	s_waitcnt lgkmcnt(0)
	s_cbranch_scc0 .Lp14_nopf
	s_mov_b32 m0, s20
	s_nop 0
	global_load_lds_dwordx4 v[88:89], off
	global_load_lds_dwordx4 v[88:89], off offset:1024
	global_load_lds_dwordx4 v[88:89], off offset:2048
	global_load_lds_dwordx4 v[88:89], off offset:3072
	s_mov_b32 m0, s21
	s_nop 0
	global_load_lds_dwordx4 v[90:91], off
	global_load_lds_dwordx4 v[90:91], off offset:1024
	global_load_lds_dwordx4 v[90:91], off offset:2048
	global_load_lds_dwordx4 v[90:91], off offset:3072
	v_lshl_add_u64 v[88:89], v[88:89], 0, s[6:7]
	v_lshl_add_u64 v[90:91], v[90:91], 0, s[6:7]
.Lp14_nopf:
	v_mov_b32_e32 v58, v28
	v_mov_b32_e32 v59, v24
	v_mov_b32_e32 v60, v29
	v_mov_b32_e32 v61, v25
	v_mov_b32_e32 v62, v30
	v_mov_b32_e32 v63, v26
	v_mov_b32_e32 v64, v31
	v_mov_b32_e32 v65, v27
	v_mov_b32_e32 v66, v21
	v_mov_b32_e32 v67, v22
	v_mov_b32_e32 v68, v20
	v_mov_b32_e32 v69, v23
	v_pk_add_f32 v[58:59], v[58:59], v[60:61]
	v_pk_add_f32 v[60:61], v[62:63], v[64:65]
	v_pk_add_f32 v[62:63], v[66:67], v[68:69]
	v_pk_add_f32 v[58:59], v[58:59], v[60:61]
	v_pk_add_f32 v[60:61], v[62:63], v[62:63] op_sel:[0,1] op_sel_hi:[1,0]
	v_add_f32_e32 v58, 0, v58
	v_add_f32_e32 v70, v16, v17
	v_add_f32_e32 v72, v18, v19
	v_mov_b32_e32 v75, v12
	v_mov_b32_e32 v71, v14
	v_mov_b32_e32 v73, v15
	v_mov_b32_e32 v61, v13
	v_add_f32_e32 v74, v58, v59
	v_mov_b32_e32 v76, v9
	v_mov_b32_e32 v77, v10
	v_mov_b32_e32 v78, v8
	v_mov_b32_e32 v79, v11
	v_pk_add_f32 v[64:65], v[70:71], v[72:73]
	v_pk_add_f32 v[58:59], v[74:75], v[60:61]
	v_pk_add_f32 v[66:67], v[76:77], v[78:79]
	v_pk_add_f32 v[58:59], v[58:59], v[64:65]
	v_pk_add_f32 v[62:63], v[66:67], v[66:67] op_sel:[0,1] op_sel_hi:[1,0]
	v_pk_add_f32 v[58:59], v[58:59], v[58:59] op_sel:[0,1] op_sel_hi:[1,0]
	v_add_f32_e32 v80, v4, v5
	v_add_f32_e32 v82, v6, v7
	v_mov_b32_e32 v81, v2
	v_mov_b32_e32 v83, v3
	v_mov_b32_e32 v63, v1
	v_mov_b32_e32 v59, v0
	v_pk_add_f32 v[68:69], v[80:81], v[82:83]
	v_pk_add_f32 v[58:59], v[58:59], v[62:63]
	s_nop 0
	v_pk_add_f32 v[58:59], v[58:59], v[68:69]
	s_nop 0
	v_add_f32_e32 v58, v58, v59
	s_nop 1
;     ...
;         if (POST) {
;             float s = 0.f;
; #pragma unroll
;             for (int j = 0; j < 8; ++j) s += (v[j].x + v[j].y) + (v[j].z + v[j].w);
;             const float mean = wave_sum(s) * (1.f / D); float s2 = 0.f;
; #pragma unroll
;             for (int j = 0; j < 8; ++j) { v[j] = v[j] - mean; s2 += (v[j].x * v[j].x + v[j].y * v[j].y) + (v[j].z * v[j].z + v[j].w * v[j].w); }
;             const float rstd = 1.f / sqrtf(wave_sum(s2) * (1.f / D) + LN_EPS);
; #pragma unroll
;             for (int j = 0; j < 8; ++j) { const f32x4 gg = ((const f32x4*)g)[F.lane + 64 * j], bb = ((const f32x4*)b)[F.lane + 64 * j]; v[j] = v[j] * rstd * gg + bb; if (WX || m >= ML) ((f32x4*)xr)[F.lane + 64 * j] = v[j]; }
	v_add_f32_dpp v58, v58, v58 quad_perm:[1,0,3,2] row_mask:0xf bank_mask:0xf bound_ctrl:1
	s_nop 1
	v_add_f32_dpp v58, v58, v58 quad_perm:[2,3,0,1] row_mask:0xf bank_mask:0xf bound_ctrl:1
	s_nop 1
	v_add_f32_dpp v58, v58, v58 row_half_mirror row_mask:0xf bank_mask:0xf bound_ctrl:1
	s_nop 1
	v_add_f32_dpp v58, v58, v58 row_mirror row_mask:0xf bank_mask:0xf bound_ctrl:1
	s_nop 1
	v_mov_b32_dpp v84, v58 row_bcast:15 row_mask:0xa bank_mask:0xf
	v_add_f32_e32 v58, v58, v84
	s_nop 1
	v_mov_b32_dpp v85, v58 row_bcast:31 row_mask:0xc bank_mask:0xf
	v_add_f32_e32 v58, v58, v85
	s_nop 0
	v_readlane_b32 s0, v58, 63
	s_nop 1
	v_fma_f32 v31, s0, v54, v31
	v_fmac_f32_e32 v29, s0, v54
	v_fma_f32 v67, s0, v54, v27
	v_fmac_f32_e32 v25, s0, v54
	v_fma_f32 v30, s0, v54, v30
	v_fma_f32 v28, s0, v54, v28
	v_fma_f32 v66, s0, v54, v26
	v_fma_f32 v24, s0, v54, v24
	v_fma_f32 v23, s0, v54, v23
	v_fmac_f32_e32 v21, s0, v54
	v_mul_f32_e32 v26, v29, v29
	v_mul_f32_e32 v27, v31, v31
	v_mul_f32_e32 v58, v25, v25
	v_mul_f32_e32 v59, v67, v67
	v_fma_f32 v22, s0, v54, v22
	v_fma_f32 v20, s0, v54, v20
	v_fma_f32 v19, s0, v54, v19
	v_fmac_f32_e32 v17, s0, v54
	v_mul_f32_e32 v60, v21, v21
	v_mul_f32_e32 v61, v23, v23
	v_fmac_f32_e32 v26, v28, v28
	v_fmac_f32_e32 v27, v30, v30
	v_fmac_f32_e32 v58, v24, v24
	v_fmac_f32_e32 v59, v66, v66
	v_fma_f32 v18, s0, v54, v18
	v_fma_f32 v16, s0, v54, v16
	v_fma_f32 v15, s0, v54, v15
	v_fmac_f32_e32 v13, s0, v54
	v_mul_f32_e32 v62, v17, v17
	v_mul_f32_e32 v63, v19, v19
	v_fmac_f32_e32 v60, v20, v20
	v_fmac_f32_e32 v61, v22, v22
	v_add_f32_e32 v26, v26, v27
	v_add_f32_e32 v27, v58, v59
	v_fma_f32 v14, s0, v54, v14
	v_fma_f32 v12, s0, v54, v12
	v_mul_f32_e32 v64, v13, v13
	v_fmac_f32_e32 v62, v16, v16
	v_fmac_f32_e32 v63, v18, v18
	v_add_f32_e32 v58, v60, v61
	v_add_f32_e32 v26, v26, v27
	v_mul_f32_e32 v27, v15, v15
	v_add_f32_e32 v59, v62, v63
	v_add_f32_e32 v26, v58, v26
	v_fmac_f32_e32 v64, v12, v12
	v_fmac_f32_e32 v27, v14, v14
	v_add_f32_e32 v26, v59, v26
	v_add_f32_e32 v27, v64, v27
	s_nop 0
	s_nop 0
	v_fma_f32 v69, s0, v54, v11
	v_fmac_f32_e32 v9, s0, v54
	v_fma_f32 v68, s0, v54, v10
	v_fma_f32 v8, s0, v54, v8
	v_mul_f32_e32 v10, v9, v9
	v_mul_f32_e32 v11, v69, v69
	v_fma_f32 v71, s0, v54, v7
	v_fmac_f32_e32 v5, s0, v54
	v_fmac_f32_e32 v10, v8, v8
	v_fmac_f32_e32 v11, v68, v68
	v_fma_f32 v70, s0, v54, v6
	v_fma_f32 v4, s0, v54, v4
	v_mul_f32_e32 v6, v5, v5
	v_mul_f32_e32 v7, v71, v71
	v_fma_f32 v73, s0, v54, v3
	v_fmac_f32_e32 v1, s0, v54
	v_add_f32_e32 v26, v27, v26
	v_add_f32_e32 v10, v10, v11
	v_fmac_f32_e32 v6, v4, v4
	v_fmac_f32_e32 v7, v70, v70
	v_fma_f32 v72, s0, v54, v2
	v_fma_f32 v0, s0, v54, v0
	v_mul_f32_e32 v2, v1, v1
	v_mul_f32_e32 v3, v73, v73
	v_add_f32_e32 v10, v10, v26
	v_add_f32_e32 v6, v6, v7
	v_fmac_f32_e32 v2, v0, v0
	v_fmac_f32_e32 v3, v72, v72
	v_add_f32_e32 v6, v6, v10
	v_add_f32_e32 v2, v2, v3
	v_add_f32_e32 v2, v2, v6
	v_mov_b32_e32 v3, 0
	s_nop 0
	v_add_f32_dpp v2, v2, v2 quad_perm:[1,0,3,2] row_mask:0xf bank_mask:0xf bound_ctrl:1
	s_nop 1
	v_add_f32_dpp v2, v2, v2 quad_perm:[2,3,0,1] row_mask:0xf bank_mask:0xf bound_ctrl:1
	s_nop 1
	v_add_f32_dpp v2, v2, v2 row_half_mirror row_mask:0xf bank_mask:0xf bound_ctrl:1
	s_nop 1
	v_add_f32_dpp v2, v2, v2 row_mirror row_mask:0xf bank_mask:0xf bound_ctrl:1
	s_nop 1
	v_mov_b32_dpp v3, v2 row_bcast:15 row_mask:0xa bank_mask:0xf
	v_add_f32_e32 v2, v2, v3
	v_mov_b32_e32 v3, 0
	s_nop 1
	v_mov_b32_dpp v3, v2 row_bcast:31 row_mask:0xc bank_mask:0xf
	v_add_f32_e32 v2, v2, v3
	s_nop 0
	v_readlane_b32 s0, v2, 63
	s_nop 1
	v_fma_f32 v2, s0, v56, v55
	v_mul_f32_e32 v3, 0x4f800000, v2
	v_cmp_gt_f32_e32 vcc, s3, v2
	s_nop 1
	v_cndmask_b32_e32 v2, v2, v3, vcc
	v_sqrt_f32_e32 v3, v2
	s_nop 0
	v_add_u32_e32 v6, -1, v3
	v_fma_f32 v7, -v6, v3, v2
	v_cmp_ge_f32_e64 s[0:1], 0, v7
	v_add_u32_e32 v7, 1, v3
	s_nop 0
	v_cndmask_b32_e64 v6, v3, v6, s[0:1]
	v_fma_f32 v3, -v7, v3, v2
	v_cmp_lt_f32_e64 s[0:1], 0, v3
	s_nop 1
	v_cndmask_b32_e64 v3, v6, v7, s[0:1]
	v_mul_f32_e32 v6, 0x37800000, v3
	v_cndmask_b32_e32 v3, v3, v6, vcc
	v_cmp_class_f32_e32 vcc, v2, v57
	s_nop 1
	v_cndmask_b32_e32 v2, v3, v2, vcc
	v_div_scale_f32 v3, s[0:1], v2, v2, 1.0
	v_rcp_f32_e32 v6, v3
	s_nop 0
	v_fma_f32 v7, -v3, v6, 1.0
	v_fmac_f32_e32 v6, v7, v6
	v_div_scale_f32 v7, vcc, 1.0, v2, 1.0
	v_mul_f32_e32 v10, v7, v6
	v_fma_f32 v11, -v3, v10, v7
	v_fmac_f32_e32 v10, v11, v6
	v_fma_f32 v3, -v3, v10, v7
	v_div_fmas_f32 v3, v3, v6, v10
	v_div_fixup_f32 v74, v3, v2, 1.0
	v_pk_mul_f32 v[2:3], v[28:29], v[74:75] op_sel_hi:[1,0]
	v_pk_mul_f32 v[6:7], v[30:31], v[74:75] op_sel_hi:[1,0]
	s_nop 0
	v_pk_fma_f32 v[26:27], v[96:97], v[2:3], v[100:101]
	v_pk_fma_f32 v[28:29], v[98:99], v[6:7], v[102:103]
	global_store_dwordx4 v[52:53], v[26:29], off offset:-4096
	s_nop 0
	s_nop 0
	s_nop 0
	v_pk_mul_f32 v[2:3], v[66:67], v[74:75] op_sel_hi:[1,0]
	v_pk_mul_f32 v[6:7], v[24:25], v[74:75] op_sel_hi:[1,0]
	v_pk_mul_f32 v[0:1], v[0:1], v[74:75] op_sel_hi:[1,0]
	s_nop 0
	v_pk_fma_f32 v[24:25], v[104:105], v[6:7], v[108:109]
	v_pk_fma_f32 v[26:27], v[106:107], v[2:3], v[110:111]
	global_store_dwordx4 v[52:53], v[24:27], off offset:-3072
	s_nop 0
	s_nop 0
	s_nop 0
	v_pk_mul_f32 v[2:3], v[22:23], v[74:75] op_sel_hi:[1,0]
	v_pk_mul_f32 v[6:7], v[20:21], v[74:75] op_sel_hi:[1,0]
	s_nop 0
	v_pk_fma_f32 v[22:23], v[2:3], v[114:115], v[118:119]
	v_pk_fma_f32 v[20:21], v[6:7], v[112:113], v[116:117]
	global_store_dwordx4 v[52:53], v[20:23], off offset:-2048
	s_nop 0
	s_nop 0
	s_nop 0
	v_pk_mul_f32 v[2:3], v[18:19], v[74:75] op_sel_hi:[1,0]
	v_pk_mul_f32 v[6:7], v[16:17], v[74:75] op_sel_hi:[1,0]
	s_nop 0
	v_pk_fma_f32 v[18:19], v[2:3], v[122:123], v[126:127]
	v_pk_fma_f32 v[16:17], v[6:7], v[120:121], v[124:125]
	global_store_dwordx4 v[52:53], v[16:19], off offset:-1024
	s_nop 0
	s_nop 0
	s_nop 0
	v_pk_mul_f32 v[2:3], v[14:15], v[74:75] op_sel_hi:[1,0]
	v_pk_mul_f32 v[6:7], v[12:13], v[74:75] op_sel_hi:[1,0]
	s_nop 0
	v_pk_fma_f32 v[12:13], v[2:3], v[130:131], v[134:135]
	v_pk_fma_f32 v[10:11], v[6:7], v[128:129], v[132:133]
	global_store_dwordx4 v[52:53], v[10:13], off
	s_nop 0
	s_nop 0
	s_nop 0
	v_pk_mul_f32 v[2:3], v[68:69], v[74:75] op_sel_hi:[1,0]
	v_pk_mul_f32 v[6:7], v[8:9], v[74:75] op_sel_hi:[1,0]
	s_nop 0
	v_pk_fma_f32 v[8:9], v[2:3], v[138:139], v[142:143]
	v_pk_fma_f32 v[6:7], v[6:7], v[136:137], v[140:141]
	global_store_dwordx4 v[52:53], v[6:9], off offset:1024
	s_nop 0
	s_nop 0
	s_nop 0
	v_pk_mul_f32 v[14:15], v[70:71], v[74:75] op_sel_hi:[1,0]
	v_pk_mul_f32 v[2:3], v[4:5], v[74:75] op_sel_hi:[1,0]
	s_nop 0
	v_pk_fma_f32 v[4:5], v[14:15], v[146:147], v[150:151]
	v_pk_fma_f32 v[2:3], v[2:3], v[144:145], v[148:149]
	global_store_dwordx4 v[52:53], v[2:5], off offset:2048
	s_nop 0
	s_nop 0
	s_nop 0
	v_pk_mul_f32 v[10:11], v[72:73], v[74:75] op_sel_hi:[1,0]
	s_nop 0
	v_pk_fma_f32 v[0:1], v[0:1], v[152:153], v[156:157]
	v_pk_fma_f32 v[2:3], v[10:11], v[154:155], v[158:159]
	global_store_dwordx4 v[52:53], v[0:3], off offset:3072
	v_lshl_add_u64 v[52:53], v[52:53], 0, s[6:7]
	s_cbranch_scc1 .LBB0_1414
